# first two phases of each tile wait vmcnt(8+E) instead of vmcnt(8): the previous epilogue stores no longer gate the new tile's first loads (in-order vmcnt); prologue ends with vmcnt(0)
# baseline (speedup 1.0000x reference)
.LBB0_156:
	s_add_u32 s12, s80, 0x1000
	s_mov_b64 s[14:15], 0x80
	s_addc_u32 s13, s81, 0
	s_and_b32 s3, s0, 3
	s_add_i32 m0, s93, 0x18000
	v_lshl_add_u64 v[8:9], v[8:9], 0, s[14:15]
	s_lshl_b32 s97, s1, 6
	s_lshl_b32 s1, s1, 13
	s_lshl_b32 s5, s3, 5
	s_lshl_b32 s17, s3, 12
	s_waitcnt vmcnt(2)
	s_barrier
	global_load_lds_dwordx4 v[8:9], off
	v_lshl_add_u64 v[6:7], v[6:7], 0, s[14:15]
	s_add_i32 m0, s93, 0x1a000
	s_add_i32 s85, s93, 0x8000
	s_add_i32 s3, s93, 0xa000
	global_load_lds_dwordx4 v[6:7], off
	v_lshl_add_u64 v[2:3], v[2:3], 0, s[14:15]
	s_mov_b32 m0, s85
	s_add_u32 s20, s70, 0x40080
	global_load_lds_dwordx4 v[2:3], off
	v_lshl_add_u64 v[2:3], v[4:5], 0, s[14:15]
	s_mov_b32 m0, s3
	s_addc_u32 s21, s71, 0
	global_load_lds_dwordx4 v[2:3], off
	s_add_i32 m0, s93, 0x1c000
	v_lshl_add_u64 v[2:3], s[20:21], 0, v[170:171]
	global_load_lds_dwordx4 v[2:3], off
	v_lshl_add_u64 v[2:3], s[20:21], 0, v[174:175]
	s_add_i32 m0, s93, 0x1e000
	v_bfe_u32 v17, v10, 4, 2
	global_load_lds_dwordx4 v[2:3], off
	v_and_b32_e32 v167, 15, v10
	v_lshlrev_b32_e32 v18, 4, v17
	v_lshlrev_b32_e32 v3, 2, v10
	v_lshl_or_b32 v2, v167, 6, v18
	v_and_b32_e32 v3, 32, v3
	s_cmpk_lt_u32 s16, 0x100
	v_bitop3_b32 v206, v2, s17, v3 bitop3:0xde
	s_cselect_b64 s[16:17], -1, 0
	s_lshl_b32 s0, s0, 4
	s_and_b32 s20, s0, 16
	v_lshlrev_b32_e32 v5, 2, v17
	v_bitop3_b32 v4, v2, s1, v3 bitop3:0xde
	v_or_b32_e32 v2, s20, v5
	v_lshlrev_b32_e32 v176, 1, v2
	v_lshlrev_b32_e32 v2, 3, v2
	v_mov_b32_e32 v3, v177
	v_lshl_add_u64 v[178:179], s[18:19], 0, v[2:3]
	v_and_b32_e32 v2, 16, v10
	v_add_u32_e32 v3, 28, v5
	v_cmp_eq_u32_e32 vcc, 0, v2
	s_and_b32 s54, s5, 64
	s_lshl_b32 s0, s54, 1
	v_cndmask_b32_e32 v2, v3, v5, vcc
	v_add_u32_e32 v184, s20, v2
	v_lshlrev_b32_e32 v2, 14, v11
	v_and_b32_e32 v2, 0xffff8000, v2
	v_lshl_add_u32 v2, v12, 11, v2
	v_and_b32_e32 v3, 1, v11
	v_lshl_or_b32 v2, v3, 6, v2
	s_mov_b64 s[18:19], s[48:49]
	v_lshl_add_u32 v186, v13, 1, v2
	v_lshlrev_b32_e32 v2, 14, v14
	s_add_u32 s0, s18, s0
	v_and_b32_e32 v2, 0xffff8000, v2
	s_waitcnt vmcnt(0)
	v_lshl_or_b32 v207, v17, 3, s5
	s_addc_u32 s1, s19, 0
	v_lshl_add_u32 v2, v15, 11, v2
	v_and_b32_e32 v3, 1, v14
	v_lshl_add_u64 v[180:181], s[0:1], 0, v[176:177]
	v_lshlrev_b32_e32 v176, 1, v207
	v_lshl_or_b32 v2, v3, 6, v2
	s_add_i32 s86, 0, 0x10000
	s_add_i32 s87, 0, 0x14000
	v_or_b32_e32 v208, 0x410, v167
	v_or_b32_e32 v209, 0x420, v167
	v_lshl_add_u64 v[182:183], s[52:53], 0, v[176:177]
	s_or_b32 s56, s54, 0x80
	v_mov_b32_e32 v187, v177
	v_lshl_add_u32 v188, v16, 1, v2
	v_mov_b32_e32 v189, v177
	v_mov_b64_e32 v[190:191], 0xb16
	v_mov_b64_e32 v[192:193], 0xb15
	v_add_u32_e32 v210, s86, v206
	v_add_u32_e32 v211, s87, v206
	v_add_u32_e32 v212, 0, v4
	s_mov_b32 s19, 0xffff
	s_mov_b32 s57, 0x10100
	s_movk_i32 s84, 0x7cf
	s_mov_b32 s18, 0x3e38aa3b
	s_mov_b64 s[20:21], 0x1dc87800
	s_mov_b64 s[22:23], 0x20000
	s_mov_b64 s[24:25], 0x24000
	s_mov_b64 s[26:27], 0x28000
	s_mov_b64 s[28:29], 0x2c000
	s_mov_b32 s92, 0
	s_barrier
	s_branch .LBB0_159

.LBB0_165:
	s_ashr_i32 s35, s34, 31
	s_lshl_b64 s[36:37], s[34:35], 19
	s_add_u32 s58, s40, s36
	s_addc_u32 s59, s41, s37
	s_and_b64 s[36:37], s[0:1], exec
	s_cselect_b32 s5, s59, s69
	s_cselect_b32 s33, s58, s68
	s_ashr_i32 s31, s30, 31
	s_lshl_b64 s[36:37], s[30:31], 19
	s_add_u32 s60, s55, s36
	s_addc_u32 s61, s88, s37
	s_and_b64 s[36:37], s[0:1], exec
	s_cselect_b32 s31, s61, s71
	s_cselect_b32 s35, s60, s70
	s_add_u32 s68, s68, 0x40080
	s_addc_u32 s69, s69, 0
	s_add_u32 s36, s70, 0x100
	s_addc_u32 s37, s71, 0
	s_mov_b32 s38, -2
	ds_read_b128 v[130:133], v210
	ds_read_b128 v[134:137], v210 offset:1024
	ds_read_b128 v[138:141], v210 offset:2048
	ds_read_b128 v[142:145], v210 offset:3072
	ds_read_b128 v[146:149], v211
	ds_read_b128 v[150:153], v211 offset:1024
	ds_read_b128 v[154:157], v211 offset:2048
	ds_read_b128 v[158:161], v211 offset:3072
	s_add_u32 s39, s68, 0xfffc0080
	s_addc_u32 s42, s69, -1
	s_cmp_eq_u32 s38, 12
	s_cselect_b32 s73, s5, s42
	s_cselect_b32 s72, s33, s39
	s_cselect_b32 s71, s31, s37
	s_cselect_b32 s70, s35, s36
	v_lshl_add_u64 v[202:203], s[68:69], 0, v[186:187]
	s_add_i32 m0, s93, 0xc000
	ds_read_b128 v[194:197], v212
	ds_read_b128 v[198:201], v212 offset:1024
	ds_read_b128 v[214:217], v212 offset:2048
	ds_read_b128 v[218:221], v212 offset:3072
	ds_read_b128 v[222:225], v212 offset:4096
	ds_read_b128 v[226:229], v212 offset:5120
	ds_read_b128 v[230:233], v212 offset:6144
	ds_read_b128 v[234:237], v212 offset:7168
	global_load_lds_dwordx4 v[202:203], off
	v_lshl_add_u64 v[202:203], s[68:69], 0, v[188:189]
	s_add_i32 m0, s93, 0xe000
	s_nop 0
	global_load_lds_dwordx4 v[202:203], off
	s_waitcnt vmcnt(20)
	s_waitcnt lgkmcnt(0)
	s_barrier
	s_setprio 1
	s_waitcnt lgkmcnt(0)
	v_mfma_f32_16x16x32_bf16 v[126:129], v[130:133], v[194:197], 0
	v_mfma_f32_16x16x32_bf16 v[122:125], v[138:141], v[194:197], 0
	v_mfma_f32_16x16x32_bf16 v[110:113], v[130:133], v[214:217], 0
	v_mfma_f32_16x16x32_bf16 v[106:109], v[138:141], v[214:217], 0
	v_mfma_f32_16x16x32_bf16 v[94:97], v[130:133], v[222:225], 0
	v_mfma_f32_16x16x32_bf16 v[90:93], v[138:141], v[222:225], 0
	v_mfma_f32_16x16x32_bf16 v[78:81], v[130:133], v[230:233], 0
	v_mfma_f32_16x16x32_bf16 v[74:77], v[138:141], v[230:233], 0
	v_mfma_f32_16x16x32_bf16 v[126:129], v[134:137], v[198:201], v[126:129]
	v_mfma_f32_16x16x32_bf16 v[122:125], v[142:145], v[198:201], v[122:125]
	v_mfma_f32_16x16x32_bf16 v[110:113], v[134:137], v[218:221], v[110:113]
	v_mfma_f32_16x16x32_bf16 v[106:109], v[142:145], v[218:221], v[106:109]
	v_mfma_f32_16x16x32_bf16 v[94:97], v[134:137], v[226:229], v[94:97]
	v_mfma_f32_16x16x32_bf16 v[90:93], v[142:145], v[226:229], v[90:93]
	v_mfma_f32_16x16x32_bf16 v[78:81], v[134:137], v[234:237], v[78:81]
	v_mfma_f32_16x16x32_bf16 v[74:77], v[142:145], v[234:237], v[74:77]
	s_setprio 0
	s_setprio 1
	v_mfma_f32_16x16x32_bf16 v[118:121], v[146:149], v[194:197], 0
	v_mfma_f32_16x16x32_bf16 v[114:117], v[154:157], v[194:197], 0
	v_mfma_f32_16x16x32_bf16 v[102:105], v[146:149], v[214:217], 0
	v_mfma_f32_16x16x32_bf16 v[98:101], v[154:157], v[214:217], 0
	v_mfma_f32_16x16x32_bf16 v[86:89], v[146:149], v[222:225], 0
	v_mfma_f32_16x16x32_bf16 v[82:85], v[154:157], v[222:225], 0
	v_mfma_f32_16x16x32_bf16 v[70:73], v[146:149], v[230:233], 0
	v_mfma_f32_16x16x32_bf16 v[66:69], v[154:157], v[230:233], 0
	v_mfma_f32_16x16x32_bf16 v[118:121], v[150:153], v[198:201], v[118:121]
	v_mfma_f32_16x16x32_bf16 v[114:117], v[158:161], v[198:201], v[114:117]
	v_mfma_f32_16x16x32_bf16 v[102:105], v[150:153], v[218:221], v[102:105]
	v_mfma_f32_16x16x32_bf16 v[98:101], v[158:161], v[218:221], v[98:101]
	v_mfma_f32_16x16x32_bf16 v[86:89], v[150:153], v[226:229], v[86:89]
	v_mfma_f32_16x16x32_bf16 v[82:85], v[158:161], v[226:229], v[82:85]
	v_mfma_f32_16x16x32_bf16 v[70:73], v[150:153], v[234:237], v[70:73]
	v_mfma_f32_16x16x32_bf16 v[66:69], v[158:161], v[234:237], v[66:69]
	s_setprio 0
	s_barrier
	s_add_i32 s39, s86, s89
	v_lshl_add_u64 v[202:203], s[70:71], 0, v[170:171]
	s_mov_b32 m0, s39
	ds_read_b128 v[194:197], v212 offset:16384
	ds_read_b128 v[198:201], v212 offset:17408
	ds_read_b128 v[214:217], v212 offset:18432
	ds_read_b128 v[218:221], v212 offset:19456
	ds_read_b128 v[222:225], v212 offset:20480
	ds_read_b128 v[226:229], v212 offset:21504
	ds_read_b128 v[230:233], v212 offset:22528
	ds_read_b128 v[234:237], v212 offset:23552
	global_load_lds_dwordx4 v[202:203], off
	s_add_i32 m0, s39, 0x2000
	s_add_u32 s42, s70, 0x40000
	v_lshl_add_u64 v[238:239], s[70:71], 0, v[174:175]
	s_addc_u32 s43, s71, 0
	s_add_i32 s39, s87, s89
	global_load_lds_dwordx4 v[238:239], off
	v_lshl_add_u64 v[240:241], s[42:43], 0, v[170:171]
	s_mov_b32 m0, s39
	v_lshl_add_u64 v[242:243], s[72:73], 0, v[172:173]
	global_load_lds_dwordx4 v[240:241], off
	v_lshl_add_u64 v[240:241], s[42:43], 0, v[174:175]
	s_add_i32 m0, s39, 0x2000
	s_nop 0
	global_load_lds_dwordx4 v[240:241], off
	v_lshl_add_u64 v[240:241], s[72:73], 0, v[168:169]
	s_mov_b32 m0, s93
	s_nop 0
	global_load_lds_dwordx4 v[240:241], off
	s_mov_b32 m0, s94
	s_nop 0
	global_load_lds_dwordx4 v[242:243], off
	s_waitcnt vmcnt(20)
	s_waitcnt lgkmcnt(0)
	s_barrier
	s_setprio 1
	s_waitcnt lgkmcnt(0)
	v_mfma_f32_16x16x32_bf16 v[62:65], v[130:133], v[194:197], 0
	v_mfma_f32_16x16x32_bf16 v[58:61], v[138:141], v[194:197], 0
	v_mfma_f32_16x16x32_bf16 v[46:49], v[130:133], v[214:217], 0
	v_mfma_f32_16x16x32_bf16 v[42:45], v[138:141], v[214:217], 0
	v_mfma_f32_16x16x32_bf16 v[30:33], v[130:133], v[222:225], 0
	v_mfma_f32_16x16x32_bf16 v[26:29], v[138:141], v[222:225], 0
	v_mfma_f32_16x16x32_bf16 v[14:17], v[130:133], v[230:233], 0
	v_mfma_f32_16x16x32_bf16 v[10:13], v[138:141], v[230:233], 0
	v_mfma_f32_16x16x32_bf16 v[62:65], v[134:137], v[198:201], v[62:65]
	v_mfma_f32_16x16x32_bf16 v[58:61], v[142:145], v[198:201], v[58:61]
	v_mfma_f32_16x16x32_bf16 v[46:49], v[134:137], v[218:221], v[46:49]
	v_mfma_f32_16x16x32_bf16 v[42:45], v[142:145], v[218:221], v[42:45]
	v_mfma_f32_16x16x32_bf16 v[30:33], v[134:137], v[226:229], v[30:33]
	v_mfma_f32_16x16x32_bf16 v[26:29], v[142:145], v[226:229], v[26:29]
	v_mfma_f32_16x16x32_bf16 v[14:17], v[134:137], v[234:237], v[14:17]
	v_mfma_f32_16x16x32_bf16 v[10:13], v[142:145], v[234:237], v[10:13]
	s_setprio 0
	s_setprio 1
	v_mfma_f32_16x16x32_bf16 v[54:57], v[146:149], v[194:197], 0
	v_mfma_f32_16x16x32_bf16 v[50:53], v[154:157], v[194:197], 0
	v_mfma_f32_16x16x32_bf16 v[38:41], v[146:149], v[214:217], 0
	v_mfma_f32_16x16x32_bf16 v[34:37], v[154:157], v[214:217], 0
	v_mfma_f32_16x16x32_bf16 v[22:25], v[146:149], v[222:225], 0
	v_mfma_f32_16x16x32_bf16 v[18:21], v[154:157], v[222:225], 0
	v_mfma_f32_16x16x32_bf16 v[6:9], v[146:149], v[230:233], 0
	v_mfma_f32_16x16x32_bf16 v[2:5], v[154:157], v[230:233], 0
	v_mfma_f32_16x16x32_bf16 v[54:57], v[150:153], v[198:201], v[54:57]
	v_mfma_f32_16x16x32_bf16 v[50:53], v[158:161], v[198:201], v[50:53]
	v_mfma_f32_16x16x32_bf16 v[38:41], v[150:153], v[218:221], v[38:41]
	v_mfma_f32_16x16x32_bf16 v[34:37], v[158:161], v[218:221], v[34:37]
	v_mfma_f32_16x16x32_bf16 v[22:25], v[150:153], v[226:229], v[22:25]
	v_mfma_f32_16x16x32_bf16 v[18:21], v[158:161], v[226:229], v[18:21]
	v_mfma_f32_16x16x32_bf16 v[6:9], v[150:153], v[234:237], v[6:9]
	v_mfma_f32_16x16x32_bf16 v[2:5], v[158:161], v[234:237], v[2:5]
	s_setprio 0
	s_barrier
	s_add_i32 s39, 0, 0x18000
	s_add_i32 s44, 0, 0x1c000
	v_add_u32_e32 v142, s39, v206
	v_add_u32_e32 v158, s44, v206
	ds_read_b128 v[130:133], v142
	ds_read_b128 v[134:137], v142 offset:1024
	ds_read_b128 v[138:141], v142 offset:2048
	ds_read_b128 v[142:145], v142 offset:3072
	ds_read_b128 v[146:149], v158
	ds_read_b128 v[150:153], v158 offset:1024
	ds_read_b128 v[154:157], v158 offset:2048
	ds_read_b128 v[158:161], v158 offset:3072
	s_add_u32 s42, s72, 0x40000
	s_addc_u32 s43, s73, 0
	s_mov_b32 m0, s95
	v_lshl_add_u64 v[244:245], s[42:43], 0, v[168:169]
	ds_read_b128 v[194:197], v212 offset:32768
	ds_read_b128 v[198:201], v212 offset:33792
	ds_read_b128 v[214:217], v212 offset:34816
	ds_read_b128 v[218:221], v212 offset:35840
	ds_read_b128 v[222:225], v212 offset:36864
	ds_read_b128 v[226:229], v212 offset:37888
	ds_read_b128 v[230:233], v212 offset:38912
	ds_read_b128 v[234:237], v212 offset:39936
	global_load_lds_dwordx4 v[244:245], off
	v_lshl_add_u64 v[244:245], s[42:43], 0, v[172:173]
	s_mov_b32 m0, s96
	s_nop 0
	global_load_lds_dwordx4 v[244:245], off
	s_waitcnt vmcnt(8)
	s_waitcnt lgkmcnt(0)
	s_barrier
	s_setprio 1
	s_waitcnt lgkmcnt(0)
	v_mfma_f32_16x16x32_bf16 v[126:129], v[130:133], v[194:197], v[126:129]
	v_mfma_f32_16x16x32_bf16 v[122:125], v[138:141], v[194:197], v[122:125]
	v_mfma_f32_16x16x32_bf16 v[110:113], v[130:133], v[214:217], v[110:113]
	v_mfma_f32_16x16x32_bf16 v[106:109], v[138:141], v[214:217], v[106:109]
	v_mfma_f32_16x16x32_bf16 v[94:97], v[130:133], v[222:225], v[94:97]
	v_mfma_f32_16x16x32_bf16 v[90:93], v[138:141], v[222:225], v[90:93]
	v_mfma_f32_16x16x32_bf16 v[78:81], v[130:133], v[230:233], v[78:81]
	v_mfma_f32_16x16x32_bf16 v[74:77], v[138:141], v[230:233], v[74:77]
	v_mfma_f32_16x16x32_bf16 v[126:129], v[134:137], v[198:201], v[126:129]
	v_mfma_f32_16x16x32_bf16 v[122:125], v[142:145], v[198:201], v[122:125]
	v_mfma_f32_16x16x32_bf16 v[110:113], v[134:137], v[218:221], v[110:113]
	v_mfma_f32_16x16x32_bf16 v[106:109], v[142:145], v[218:221], v[106:109]
	v_mfma_f32_16x16x32_bf16 v[94:97], v[134:137], v[226:229], v[94:97]
	v_mfma_f32_16x16x32_bf16 v[90:93], v[142:145], v[226:229], v[90:93]
	v_mfma_f32_16x16x32_bf16 v[78:81], v[134:137], v[234:237], v[78:81]
	v_mfma_f32_16x16x32_bf16 v[74:77], v[142:145], v[234:237], v[74:77]
	s_setprio 0
	s_setprio 1
	v_mfma_f32_16x16x32_bf16 v[118:121], v[146:149], v[194:197], v[118:121]
	v_mfma_f32_16x16x32_bf16 v[114:117], v[154:157], v[194:197], v[114:117]
	v_mfma_f32_16x16x32_bf16 v[102:105], v[146:149], v[214:217], v[102:105]
	v_mfma_f32_16x16x32_bf16 v[98:101], v[154:157], v[214:217], v[98:101]
	v_mfma_f32_16x16x32_bf16 v[86:89], v[146:149], v[222:225], v[86:89]
	v_mfma_f32_16x16x32_bf16 v[82:85], v[154:157], v[222:225], v[82:85]
	v_mfma_f32_16x16x32_bf16 v[70:73], v[146:149], v[230:233], v[70:73]
	v_mfma_f32_16x16x32_bf16 v[66:69], v[154:157], v[230:233], v[66:69]
	v_mfma_f32_16x16x32_bf16 v[118:121], v[150:153], v[198:201], v[118:121]
	v_mfma_f32_16x16x32_bf16 v[114:117], v[158:161], v[198:201], v[114:117]
	v_mfma_f32_16x16x32_bf16 v[102:105], v[150:153], v[218:221], v[102:105]
	v_mfma_f32_16x16x32_bf16 v[98:101], v[158:161], v[218:221], v[98:101]
	v_mfma_f32_16x16x32_bf16 v[86:89], v[150:153], v[226:229], v[86:89]
	v_mfma_f32_16x16x32_bf16 v[82:85], v[158:161], v[226:229], v[82:85]
	v_mfma_f32_16x16x32_bf16 v[70:73], v[150:153], v[234:237], v[70:73]
	v_mfma_f32_16x16x32_bf16 v[66:69], v[158:161], v[234:237], v[66:69]
	s_setprio 0
	s_barrier
	s_add_i32 s39, s39, s89
	v_lshl_add_u64 v[202:203], v[202:203], 0, s[14:15]
	s_mov_b32 m0, s39
	ds_read_b128 v[194:197], v212 offset:49152
	ds_read_b128 v[198:201], v212 offset:50176
	ds_read_b128 v[214:217], v212 offset:51200
	ds_read_b128 v[218:221], v212 offset:52224
	ds_read_b128 v[222:225], v212 offset:53248
	ds_read_b128 v[226:229], v212 offset:54272
	ds_read_b128 v[230:233], v212 offset:55296
	ds_read_b128 v[234:237], v212 offset:56320
	global_load_lds_dwordx4 v[202:203], off
	s_add_i32 m0, s39, 0x2000
	s_add_u32 s42, s70, 0x40080
	v_lshl_add_u64 v[202:203], v[238:239], 0, s[14:15]
	s_addc_u32 s43, s71, 0
	s_add_i32 s39, s44, s89
	global_load_lds_dwordx4 v[202:203], off
	v_lshl_add_u64 v[202:203], s[42:43], 0, v[170:171]
	s_mov_b32 m0, s39
	s_nop 0
	global_load_lds_dwordx4 v[202:203], off
	v_lshl_add_u64 v[202:203], s[42:43], 0, v[174:175]
	s_add_i32 m0, s39, 0x2000
	s_nop 0
	global_load_lds_dwordx4 v[202:203], off
	v_lshl_add_u64 v[202:203], v[240:241], 0, s[14:15]
	s_mov_b32 m0, s85
	s_nop 0
	global_load_lds_dwordx4 v[202:203], off
	v_lshl_add_u64 v[202:203], v[242:243], 0, s[14:15]
	s_mov_b32 m0, s3
	s_nop 0
	global_load_lds_dwordx4 v[202:203], off
	s_waitcnt vmcnt(8)
	s_waitcnt lgkmcnt(0)
	s_barrier
	s_setprio 1
	s_waitcnt lgkmcnt(0)
	v_mfma_f32_16x16x32_bf16 v[62:65], v[130:133], v[194:197], v[62:65]
	v_mfma_f32_16x16x32_bf16 v[58:61], v[138:141], v[194:197], v[58:61]
	v_mfma_f32_16x16x32_bf16 v[46:49], v[130:133], v[214:217], v[46:49]
	v_mfma_f32_16x16x32_bf16 v[42:45], v[138:141], v[214:217], v[42:45]
	v_mfma_f32_16x16x32_bf16 v[30:33], v[130:133], v[222:225], v[30:33]
	v_mfma_f32_16x16x32_bf16 v[26:29], v[138:141], v[222:225], v[26:29]
	v_mfma_f32_16x16x32_bf16 v[14:17], v[130:133], v[230:233], v[14:17]
	v_mfma_f32_16x16x32_bf16 v[10:13], v[138:141], v[230:233], v[10:13]
	v_mfma_f32_16x16x32_bf16 v[62:65], v[134:137], v[198:201], v[62:65]
	v_mfma_f32_16x16x32_bf16 v[58:61], v[142:145], v[198:201], v[58:61]
	v_mfma_f32_16x16x32_bf16 v[46:49], v[134:137], v[218:221], v[46:49]
	v_mfma_f32_16x16x32_bf16 v[42:45], v[142:145], v[218:221], v[42:45]
	v_mfma_f32_16x16x32_bf16 v[30:33], v[134:137], v[226:229], v[30:33]
	v_mfma_f32_16x16x32_bf16 v[26:29], v[142:145], v[226:229], v[26:29]
	v_mfma_f32_16x16x32_bf16 v[14:17], v[134:137], v[234:237], v[14:17]
	v_mfma_f32_16x16x32_bf16 v[10:13], v[142:145], v[234:237], v[10:13]
	s_setprio 0
	s_setprio 1
	v_mfma_f32_16x16x32_bf16 v[54:57], v[146:149], v[194:197], v[54:57]
	v_mfma_f32_16x16x32_bf16 v[50:53], v[154:157], v[194:197], v[50:53]
	v_mfma_f32_16x16x32_bf16 v[38:41], v[146:149], v[214:217], v[38:41]
	v_mfma_f32_16x16x32_bf16 v[34:37], v[154:157], v[214:217], v[34:37]
	v_mfma_f32_16x16x32_bf16 v[22:25], v[146:149], v[222:225], v[22:25]
	v_mfma_f32_16x16x32_bf16 v[18:21], v[154:157], v[222:225], v[18:21]
	v_mfma_f32_16x16x32_bf16 v[6:9], v[146:149], v[230:233], v[6:9]
	v_mfma_f32_16x16x32_bf16 v[2:5], v[154:157], v[230:233], v[2:5]
	v_mfma_f32_16x16x32_bf16 v[54:57], v[150:153], v[198:201], v[54:57]
	v_mfma_f32_16x16x32_bf16 v[50:53], v[158:161], v[198:201], v[50:53]
	v_mfma_f32_16x16x32_bf16 v[38:41], v[150:153], v[218:221], v[38:41]
	v_mfma_f32_16x16x32_bf16 v[34:37], v[158:161], v[218:221], v[34:37]
	v_mfma_f32_16x16x32_bf16 v[22:25], v[150:153], v[226:229], v[22:25]
	v_mfma_f32_16x16x32_bf16 v[18:21], v[158:161], v[226:229], v[18:21]
	v_mfma_f32_16x16x32_bf16 v[6:9], v[150:153], v[234:237], v[6:9]
	v_mfma_f32_16x16x32_bf16 v[2:5], v[158:161], v[234:237], v[2:5]
	s_setprio 0
	s_barrier
	s_add_i32 s38, s38, 2
	s_add_u32 s68, s68, 0x100
	s_addc_u32 s69, s69, 0
	s_add_u32 s36, s36, 0x100
	s_addc_u32 s37, s37, 0

.LBB0_505:
	s_add_u32 s8, s80, 0xc3000
	s_addc_u32 s9, s81, 0
	s_add_u32 s12, s80, 0x103800
	s_addc_u32 s13, s81, 0
	s_lshl_b32 s5, s5, 5
	s_mov_b64 s[14:15], 0x80
	s_and_b32 s18, s5, 0x60
	s_add_i32 m0, s29, 0x18000
	v_lshl_add_u64 v[8:9], v[8:9], 0, s[14:15]
	s_lshl_b32 s7, s4, 13
	s_lshl_b32 s5, s18, 7
	s_waitcnt vmcnt(2)
	s_barrier
	global_load_lds_dwordx4 v[8:9], off
	v_lshl_add_u64 v[6:7], v[6:7], 0, s[14:15]
	s_add_i32 m0, s29, 0x1a000
	s_add_i32 s52, s29, 0x8000
	s_add_i32 s53, s29, 0xa000
	global_load_lds_dwordx4 v[6:7], off
	v_lshl_add_u64 v[2:3], v[2:3], 0, s[14:15]
	s_mov_b32 m0, s52
	s_add_u32 s16, s38, 0x40080
	global_load_lds_dwordx4 v[2:3], off
	v_lshl_add_u64 v[2:3], v[4:5], 0, s[14:15]
	s_mov_b32 m0, s53
	s_addc_u32 s17, s39, 0
	global_load_lds_dwordx4 v[2:3], off
	s_add_i32 m0, s29, 0x1c000
	v_lshl_add_u64 v[2:3], s[16:17], 0, v[174:175]
	global_load_lds_dwordx4 v[2:3], off
	v_lshl_add_u64 v[2:3], s[16:17], 0, v[178:179]
	s_add_i32 m0, s29, 0x1e000
	s_cmpk_lt_u32 s6, 0x100
	global_load_lds_dwordx4 v[2:3], off
	v_bfe_u32 v3, v10, 4, 2
	v_and_b32_e32 v2, 15, v10
	v_lshlrev_b32_e32 v4, 4, v3
	v_lshl_or_b32 v1, s4, 6, v2
	v_lshl_or_b32 v2, v2, 6, v4
	v_lshlrev_b32_e32 v4, 2, v10
	v_and_b32_e32 v4, 32, v4
	v_bitop3_b32 v5, v2, s7, v4 bitop3:0xde
	v_bitop3_b32 v171, v2, s5, v4 bitop3:0xde
	v_lshlrev_b32_e32 v2, 14, v11
	v_and_b32_e32 v2, 0xffff8000, v2
	v_cmp_eq_u32_e64 s[4:5], 0, v3
	v_lshl_or_b32 v189, v3, 3, s18
	v_lshl_add_u32 v2, v12, 11, v2
	v_and_b32_e32 v3, 1, v11
	v_lshl_or_b32 v2, v3, 6, v2
	v_lshl_add_u32 v180, v13, 1, v2
	v_lshlrev_b32_e32 v2, 14, v14
	v_and_b32_e32 v2, 0xffff8000, v2
	s_waitcnt vmcnt(0)
	v_lshl_add_u32 v2, v15, 11, v2
	v_and_b32_e32 v3, 1, v14
	s_cselect_b64 s[16:17], -1, 0
	v_lshl_or_b32 v2, v3, 6, v2
	s_add_i32 s55, 0, 0x10000
	s_add_i32 s56, 0, 0x14000
	v_mov_b32_e32 v181, v175
	v_lshl_add_u32 v182, v16, 1, v2
	v_mov_b32_e32 v183, v175
	v_mov_b64_e32 v[184:185], 0x404
	v_mov_b64_e32 v[186:187], 0x403
	v_add_u32_e32 v193, s55, v171
	v_add_u32_e32 v195, s56, v171
	v_add_u32_e32 v197, 0, v5
	s_barrier
	s_branch .LBB0_508

.LBB0_514:
	s_ashr_i32 s21, s20, 31
	s_lshl_b64 s[22:23], s[20:21], 19
	s_add_u32 s22, s10, s22
	s_addc_u32 s23, s11, s23
	s_and_b64 s[24:25], s[6:7], exec
	s_cselect_b32 s21, s23, s31
	s_cselect_b32 s27, s22, s30
	s_ashr_i32 s19, s18, 31
	s_lshl_b64 s[24:25], s[18:19], 19
	s_add_u32 s24, s3, s24
	s_addc_u32 s25, s46, s25
	s_and_b64 s[36:37], s[6:7], exec
	s_cselect_b32 s19, s25, s39
	s_cselect_b32 s33, s24, s38
	s_add_u32 s30, s30, 0x40080
	s_addc_u32 s31, s31, 0
	s_add_u32 s36, s38, 0x100
	s_addc_u32 s37, s39, 0
	s_mov_b32 s54, -2
	s_waitcnt lgkmcnt(0)
	s_waitcnt vmcnt(0)
	ds_read_b128 v[82:85], v193
	ds_read_b128 v[86:89], v193 offset:1024
	ds_read_b128 v[98:101], v193 offset:2048
	ds_read_b128 v[102:105], v193 offset:3072
	ds_read_b128 v[146:149], v195
	ds_read_b128 v[150:153], v195 offset:1024
	ds_read_b128 v[154:157], v195 offset:2048
	ds_read_b128 v[158:161], v195 offset:3072
	s_add_u32 s38, s30, 0xfffc0080
	s_addc_u32 s39, s31, -1
	s_cmp_eq_u32 s54, 12
	s_cselect_b32 s45, s21, s39
	s_cselect_b32 s44, s27, s38
	s_cselect_b32 s39, s19, s37
	s_cselect_b32 s38, s33, s36
	v_lshl_add_u64 v[190:191], s[30:31], 0, v[180:181]
	s_add_i32 m0, s29, 0xc000
	ds_read_b128 v[162:165], v197
	ds_read_b128 v[166:169], v197 offset:1024
	ds_read_b128 v[198:201], v197 offset:2048
	ds_read_b128 v[202:205], v197 offset:3072
	ds_read_b128 v[206:209], v197 offset:4096
	ds_read_b128 v[212:215], v197 offset:5120
	ds_read_b128 v[216:219], v197 offset:6144
	ds_read_b128 v[220:223], v197 offset:7168
	global_load_lds_dwordx4 v[190:191], off
	v_lshl_add_u64 v[190:191], s[30:31], 0, v[182:183]
	s_add_i32 m0, s29, 0xe000
	s_nop 0
	global_load_lds_dwordx4 v[190:191], off
	s_waitcnt vmcnt(48)
	s_waitcnt lgkmcnt(0)
	s_barrier
	s_setprio 1
	s_waitcnt lgkmcnt(0)
	v_mfma_f32_16x16x32_bf16 v[142:145], v[82:85], v[162:165], 0
	v_mfma_f32_16x16x32_bf16 v[138:141], v[98:101], v[162:165], 0
	v_mfma_f32_16x16x32_bf16 v[126:129], v[82:85], v[198:201], 0
	v_mfma_f32_16x16x32_bf16 v[122:125], v[98:101], v[198:201], 0
	v_mfma_f32_16x16x32_bf16 v[110:113], v[82:85], v[206:209], 0
	v_mfma_f32_16x16x32_bf16 v[106:109], v[98:101], v[206:209], 0
	v_mfma_f32_16x16x32_bf16 v[78:81], v[82:85], v[216:219], 0
	v_mfma_f32_16x16x32_bf16 v[74:77], v[98:101], v[216:219], 0
	v_mfma_f32_16x16x32_bf16 v[142:145], v[86:89], v[166:169], v[142:145]
	v_mfma_f32_16x16x32_bf16 v[138:141], v[102:105], v[166:169], v[138:141]
	v_mfma_f32_16x16x32_bf16 v[126:129], v[86:89], v[202:205], v[126:129]
	v_mfma_f32_16x16x32_bf16 v[122:125], v[102:105], v[202:205], v[122:125]
	v_mfma_f32_16x16x32_bf16 v[110:113], v[86:89], v[212:215], v[110:113]
	v_mfma_f32_16x16x32_bf16 v[106:109], v[102:105], v[212:215], v[106:109]
	v_mfma_f32_16x16x32_bf16 v[78:81], v[86:89], v[220:223], v[78:81]
	v_mfma_f32_16x16x32_bf16 v[74:77], v[102:105], v[220:223], v[74:77]
	s_setprio 0
	s_setprio 1
	v_mfma_f32_16x16x32_bf16 v[134:137], v[146:149], v[162:165], 0
	v_mfma_f32_16x16x32_bf16 v[130:133], v[154:157], v[162:165], 0
	v_mfma_f32_16x16x32_bf16 v[118:121], v[146:149], v[198:201], 0
	v_mfma_f32_16x16x32_bf16 v[114:117], v[154:157], v[198:201], 0
	v_mfma_f32_16x16x32_bf16 v[94:97], v[146:149], v[206:209], 0
	v_mfma_f32_16x16x32_bf16 v[90:93], v[154:157], v[206:209], 0
	v_mfma_f32_16x16x32_bf16 v[70:73], v[146:149], v[216:219], 0
	v_mfma_f32_16x16x32_bf16 v[66:69], v[154:157], v[216:219], 0
	v_mfma_f32_16x16x32_bf16 v[134:137], v[150:153], v[166:169], v[134:137]
	v_mfma_f32_16x16x32_bf16 v[130:133], v[158:161], v[166:169], v[130:133]
	v_mfma_f32_16x16x32_bf16 v[118:121], v[150:153], v[202:205], v[118:121]
	v_mfma_f32_16x16x32_bf16 v[114:117], v[158:161], v[202:205], v[114:117]
	v_mfma_f32_16x16x32_bf16 v[94:97], v[150:153], v[212:215], v[94:97]
	v_mfma_f32_16x16x32_bf16 v[90:93], v[158:161], v[212:215], v[90:93]
	v_mfma_f32_16x16x32_bf16 v[70:73], v[150:153], v[220:223], v[70:73]
	v_mfma_f32_16x16x32_bf16 v[66:69], v[158:161], v[220:223], v[66:69]
	s_setprio 0
	s_barrier
	s_add_i32 s42, s55, s47
	v_lshl_add_u64 v[190:191], s[38:39], 0, v[174:175]
	s_mov_b32 m0, s42
	ds_read_b128 v[162:165], v197 offset:16384
	ds_read_b128 v[166:169], v197 offset:17408
	ds_read_b128 v[198:201], v197 offset:18432
	ds_read_b128 v[202:205], v197 offset:19456
	ds_read_b128 v[206:209], v197 offset:20480
	ds_read_b128 v[212:215], v197 offset:21504
	ds_read_b128 v[216:219], v197 offset:22528
	ds_read_b128 v[220:223], v197 offset:23552
	global_load_lds_dwordx4 v[190:191], off
	s_add_i32 m0, s42, 0x2000
	s_add_u32 s42, s38, 0x40000
	v_lshl_add_u64 v[224:225], s[38:39], 0, v[178:179]
	s_addc_u32 s43, s39, 0
	s_add_i32 s57, s56, s47
	global_load_lds_dwordx4 v[224:225], off
	v_lshl_add_u64 v[226:227], s[42:43], 0, v[174:175]
	s_mov_b32 m0, s57
	v_lshl_add_u64 v[228:229], s[44:45], 0, v[176:177]
	global_load_lds_dwordx4 v[226:227], off
	v_lshl_add_u64 v[226:227], s[42:43], 0, v[178:179]
	s_add_i32 m0, s57, 0x2000
	s_nop 0
	global_load_lds_dwordx4 v[226:227], off
	v_lshl_add_u64 v[226:227], s[44:45], 0, v[172:173]
	s_mov_b32 m0, s29
	s_nop 0
	global_load_lds_dwordx4 v[226:227], off
	s_mov_b32 m0, s48
	s_nop 0
	global_load_lds_dwordx4 v[228:229], off
	s_waitcnt vmcnt(48)
	s_waitcnt lgkmcnt(0)
	s_barrier
	s_setprio 1
	s_waitcnt lgkmcnt(0)
	v_mfma_f32_16x16x32_bf16 v[62:65], v[82:85], v[162:165], 0
	v_mfma_f32_16x16x32_bf16 v[58:61], v[98:101], v[162:165], 0
	v_mfma_f32_16x16x32_bf16 v[46:49], v[82:85], v[198:201], 0
	v_mfma_f32_16x16x32_bf16 v[42:45], v[98:101], v[198:201], 0
	v_mfma_f32_16x16x32_bf16 v[30:33], v[82:85], v[206:209], 0
	v_mfma_f32_16x16x32_bf16 v[26:29], v[98:101], v[206:209], 0
	v_mfma_f32_16x16x32_bf16 v[14:17], v[82:85], v[216:219], 0
	v_mfma_f32_16x16x32_bf16 v[10:13], v[98:101], v[216:219], 0
	v_mfma_f32_16x16x32_bf16 v[62:65], v[86:89], v[166:169], v[62:65]
	v_mfma_f32_16x16x32_bf16 v[58:61], v[102:105], v[166:169], v[58:61]
	v_mfma_f32_16x16x32_bf16 v[46:49], v[86:89], v[202:205], v[46:49]
	v_mfma_f32_16x16x32_bf16 v[42:45], v[102:105], v[202:205], v[42:45]
	v_mfma_f32_16x16x32_bf16 v[30:33], v[86:89], v[212:215], v[30:33]
	v_mfma_f32_16x16x32_bf16 v[26:29], v[102:105], v[212:215], v[26:29]
	v_mfma_f32_16x16x32_bf16 v[14:17], v[86:89], v[220:223], v[14:17]
	v_mfma_f32_16x16x32_bf16 v[10:13], v[102:105], v[220:223], v[10:13]
	s_setprio 0
	s_setprio 1
	v_mfma_f32_16x16x32_bf16 v[54:57], v[146:149], v[162:165], 0
	v_mfma_f32_16x16x32_bf16 v[50:53], v[154:157], v[162:165], 0
	v_mfma_f32_16x16x32_bf16 v[38:41], v[146:149], v[198:201], 0
	v_mfma_f32_16x16x32_bf16 v[34:37], v[154:157], v[198:201], 0
	v_mfma_f32_16x16x32_bf16 v[22:25], v[146:149], v[206:209], 0
	v_mfma_f32_16x16x32_bf16 v[18:21], v[154:157], v[206:209], 0
	v_mfma_f32_16x16x32_bf16 v[6:9], v[146:149], v[216:219], 0
	v_mfma_f32_16x16x32_bf16 v[2:5], v[154:157], v[216:219], 0
	v_mfma_f32_16x16x32_bf16 v[54:57], v[150:153], v[166:169], v[54:57]
	v_mfma_f32_16x16x32_bf16 v[50:53], v[158:161], v[166:169], v[50:53]
	v_mfma_f32_16x16x32_bf16 v[38:41], v[150:153], v[202:205], v[38:41]
	v_mfma_f32_16x16x32_bf16 v[34:37], v[158:161], v[202:205], v[34:37]
	v_mfma_f32_16x16x32_bf16 v[22:25], v[150:153], v[212:215], v[22:25]
	v_mfma_f32_16x16x32_bf16 v[18:21], v[158:161], v[212:215], v[18:21]
	v_mfma_f32_16x16x32_bf16 v[6:9], v[150:153], v[220:223], v[6:9]
	v_mfma_f32_16x16x32_bf16 v[2:5], v[158:161], v[220:223], v[2:5]
	s_setprio 0
	s_barrier
	s_add_i32 s57, 0, 0x18000
	s_add_i32 s58, 0, 0x1c000
	v_add_u32_e32 v102, s57, v171
	v_add_u32_e32 v158, s58, v171
	ds_read_b128 v[82:85], v102
	ds_read_b128 v[86:89], v102 offset:1024
	ds_read_b128 v[98:101], v102 offset:2048
	ds_read_b128 v[102:105], v102 offset:3072
	ds_read_b128 v[146:149], v158
	ds_read_b128 v[150:153], v158 offset:1024
	ds_read_b128 v[154:157], v158 offset:2048
	ds_read_b128 v[158:161], v158 offset:3072
	s_add_u32 s42, s44, 0x40000
	s_addc_u32 s43, s45, 0
	s_mov_b32 m0, s49
	v_lshl_add_u64 v[230:231], s[42:43], 0, v[172:173]
	ds_read_b128 v[162:165], v197 offset:32768
	ds_read_b128 v[166:169], v197 offset:33792
	ds_read_b128 v[198:201], v197 offset:34816
	ds_read_b128 v[202:205], v197 offset:35840
	ds_read_b128 v[206:209], v197 offset:36864
	ds_read_b128 v[212:215], v197 offset:37888
	ds_read_b128 v[216:219], v197 offset:38912
	ds_read_b128 v[220:223], v197 offset:39936
	global_load_lds_dwordx4 v[230:231], off
	v_lshl_add_u64 v[230:231], s[42:43], 0, v[176:177]
	s_mov_b32 m0, s50
	s_nop 0
	global_load_lds_dwordx4 v[230:231], off
	s_waitcnt vmcnt(8)
	s_waitcnt lgkmcnt(0)
	s_barrier
	s_setprio 1
	s_waitcnt lgkmcnt(0)
	v_mfma_f32_16x16x32_bf16 v[142:145], v[82:85], v[162:165], v[142:145]
	v_mfma_f32_16x16x32_bf16 v[138:141], v[98:101], v[162:165], v[138:141]
	v_mfma_f32_16x16x32_bf16 v[126:129], v[82:85], v[198:201], v[126:129]
	v_mfma_f32_16x16x32_bf16 v[122:125], v[98:101], v[198:201], v[122:125]
	v_mfma_f32_16x16x32_bf16 v[110:113], v[82:85], v[206:209], v[110:113]
	v_mfma_f32_16x16x32_bf16 v[106:109], v[98:101], v[206:209], v[106:109]
	v_mfma_f32_16x16x32_bf16 v[78:81], v[82:85], v[216:219], v[78:81]
	v_mfma_f32_16x16x32_bf16 v[74:77], v[98:101], v[216:219], v[74:77]
	v_mfma_f32_16x16x32_bf16 v[142:145], v[86:89], v[166:169], v[142:145]
	v_mfma_f32_16x16x32_bf16 v[138:141], v[102:105], v[166:169], v[138:141]
	v_mfma_f32_16x16x32_bf16 v[126:129], v[86:89], v[202:205], v[126:129]
	v_mfma_f32_16x16x32_bf16 v[122:125], v[102:105], v[202:205], v[122:125]
	v_mfma_f32_16x16x32_bf16 v[110:113], v[86:89], v[212:215], v[110:113]
	v_mfma_f32_16x16x32_bf16 v[106:109], v[102:105], v[212:215], v[106:109]
	v_mfma_f32_16x16x32_bf16 v[78:81], v[86:89], v[220:223], v[78:81]
	v_mfma_f32_16x16x32_bf16 v[74:77], v[102:105], v[220:223], v[74:77]
	s_setprio 0
	s_setprio 1
	v_mfma_f32_16x16x32_bf16 v[134:137], v[146:149], v[162:165], v[134:137]
	v_mfma_f32_16x16x32_bf16 v[130:133], v[154:157], v[162:165], v[130:133]
	v_mfma_f32_16x16x32_bf16 v[118:121], v[146:149], v[198:201], v[118:121]
	v_mfma_f32_16x16x32_bf16 v[114:117], v[154:157], v[198:201], v[114:117]
	v_mfma_f32_16x16x32_bf16 v[94:97], v[146:149], v[206:209], v[94:97]
	v_mfma_f32_16x16x32_bf16 v[90:93], v[154:157], v[206:209], v[90:93]
	v_mfma_f32_16x16x32_bf16 v[70:73], v[146:149], v[216:219], v[70:73]
	v_mfma_f32_16x16x32_bf16 v[66:69], v[154:157], v[216:219], v[66:69]
	v_mfma_f32_16x16x32_bf16 v[134:137], v[150:153], v[166:169], v[134:137]
	v_mfma_f32_16x16x32_bf16 v[130:133], v[158:161], v[166:169], v[130:133]
	v_mfma_f32_16x16x32_bf16 v[118:121], v[150:153], v[202:205], v[118:121]
	v_mfma_f32_16x16x32_bf16 v[114:117], v[158:161], v[202:205], v[114:117]
	v_mfma_f32_16x16x32_bf16 v[94:97], v[150:153], v[212:215], v[94:97]
	v_mfma_f32_16x16x32_bf16 v[90:93], v[158:161], v[212:215], v[90:93]
	v_mfma_f32_16x16x32_bf16 v[70:73], v[150:153], v[220:223], v[70:73]
	v_mfma_f32_16x16x32_bf16 v[66:69], v[158:161], v[220:223], v[66:69]
	s_setprio 0
	s_barrier
	s_add_i32 s42, s57, s47
	v_lshl_add_u64 v[190:191], v[190:191], 0, s[14:15]
	s_mov_b32 m0, s42
	ds_read_b128 v[162:165], v197 offset:49152
	ds_read_b128 v[166:169], v197 offset:50176
	ds_read_b128 v[198:201], v197 offset:51200
	ds_read_b128 v[202:205], v197 offset:52224
	ds_read_b128 v[206:209], v197 offset:53248
	ds_read_b128 v[212:215], v197 offset:54272
	ds_read_b128 v[216:219], v197 offset:55296
	ds_read_b128 v[220:223], v197 offset:56320
	global_load_lds_dwordx4 v[190:191], off
	s_add_i32 m0, s42, 0x2000
	s_add_u32 s38, s38, 0x40080
	v_lshl_add_u64 v[190:191], v[224:225], 0, s[14:15]
	s_addc_u32 s39, s39, 0
	s_add_i32 s42, s58, s47
	global_load_lds_dwordx4 v[190:191], off
	v_lshl_add_u64 v[190:191], s[38:39], 0, v[174:175]
	s_mov_b32 m0, s42
	s_nop 0
	global_load_lds_dwordx4 v[190:191], off
	v_lshl_add_u64 v[190:191], s[38:39], 0, v[178:179]
	s_add_i32 m0, s42, 0x2000
	s_nop 0
	global_load_lds_dwordx4 v[190:191], off
	v_lshl_add_u64 v[190:191], v[226:227], 0, s[14:15]
	s_mov_b32 m0, s52
	s_nop 0
	global_load_lds_dwordx4 v[190:191], off
	v_lshl_add_u64 v[190:191], v[228:229], 0, s[14:15]
	s_mov_b32 m0, s53
	s_nop 0
	global_load_lds_dwordx4 v[190:191], off
	s_waitcnt vmcnt(8)
	s_waitcnt lgkmcnt(0)
	s_barrier
	s_setprio 1
	s_waitcnt lgkmcnt(0)
	v_mfma_f32_16x16x32_bf16 v[62:65], v[82:85], v[162:165], v[62:65]
	v_mfma_f32_16x16x32_bf16 v[58:61], v[98:101], v[162:165], v[58:61]
	v_mfma_f32_16x16x32_bf16 v[46:49], v[82:85], v[198:201], v[46:49]
	v_mfma_f32_16x16x32_bf16 v[42:45], v[98:101], v[198:201], v[42:45]
	v_mfma_f32_16x16x32_bf16 v[30:33], v[82:85], v[206:209], v[30:33]
	v_mfma_f32_16x16x32_bf16 v[26:29], v[98:101], v[206:209], v[26:29]
	v_mfma_f32_16x16x32_bf16 v[14:17], v[82:85], v[216:219], v[14:17]
	v_mfma_f32_16x16x32_bf16 v[10:13], v[98:101], v[216:219], v[10:13]
	v_mfma_f32_16x16x32_bf16 v[62:65], v[86:89], v[166:169], v[62:65]
	v_mfma_f32_16x16x32_bf16 v[58:61], v[102:105], v[166:169], v[58:61]
	v_mfma_f32_16x16x32_bf16 v[46:49], v[86:89], v[202:205], v[46:49]
	v_mfma_f32_16x16x32_bf16 v[42:45], v[102:105], v[202:205], v[42:45]
	v_mfma_f32_16x16x32_bf16 v[30:33], v[86:89], v[212:215], v[30:33]
	v_mfma_f32_16x16x32_bf16 v[26:29], v[102:105], v[212:215], v[26:29]
	v_mfma_f32_16x16x32_bf16 v[14:17], v[86:89], v[220:223], v[14:17]
	v_mfma_f32_16x16x32_bf16 v[10:13], v[102:105], v[220:223], v[10:13]
	s_setprio 0
	s_setprio 1
	v_mfma_f32_16x16x32_bf16 v[54:57], v[146:149], v[162:165], v[54:57]
	v_mfma_f32_16x16x32_bf16 v[50:53], v[154:157], v[162:165], v[50:53]
	v_mfma_f32_16x16x32_bf16 v[38:41], v[146:149], v[198:201], v[38:41]
	v_mfma_f32_16x16x32_bf16 v[34:37], v[154:157], v[198:201], v[34:37]
	v_mfma_f32_16x16x32_bf16 v[22:25], v[146:149], v[206:209], v[22:25]
	v_mfma_f32_16x16x32_bf16 v[18:21], v[154:157], v[206:209], v[18:21]
	v_mfma_f32_16x16x32_bf16 v[6:9], v[146:149], v[216:219], v[6:9]
	v_mfma_f32_16x16x32_bf16 v[2:5], v[154:157], v[216:219], v[2:5]
	v_mfma_f32_16x16x32_bf16 v[54:57], v[150:153], v[166:169], v[54:57]
	v_mfma_f32_16x16x32_bf16 v[50:53], v[158:161], v[166:169], v[50:53]
	v_mfma_f32_16x16x32_bf16 v[38:41], v[150:153], v[202:205], v[38:41]
	v_mfma_f32_16x16x32_bf16 v[34:37], v[158:161], v[202:205], v[34:37]
	v_mfma_f32_16x16x32_bf16 v[22:25], v[150:153], v[212:215], v[22:25]
	v_mfma_f32_16x16x32_bf16 v[18:21], v[158:161], v[212:215], v[18:21]
	v_mfma_f32_16x16x32_bf16 v[6:9], v[150:153], v[220:223], v[6:9]
	v_mfma_f32_16x16x32_bf16 v[2:5], v[158:161], v[220:223], v[2:5]
	s_setprio 0
	s_barrier
	s_add_i32 s54, s54, 2
	s_add_u32 s30, s30, 0x100
	s_addc_u32 s31, s31, 0
	s_add_u32 s36, s36, 0x100
	s_addc_u32 s37, s37, 0

.LBB0_596:
	s_and_b32 s16, s12, 3
	s_mov_b64 s[12:13], 0x80
	s_add_i32 m0, s44, 0x18000
	v_lshl_add_u64 v[8:9], v[8:9], 0, s[12:13]
	s_lshl_b32 s15, s14, 13
	s_lshl_b32 s18, s16, 12
	s_waitcnt vmcnt(2)
	s_barrier
	global_load_lds_dwordx4 v[8:9], off
	v_lshl_add_u64 v[6:7], v[6:7], 0, s[12:13]
	s_add_i32 m0, s44, 0x1a000
	s_add_i32 s48, s44, 0x8000
	s_add_i32 s49, s44, 0xa000
	global_load_lds_dwordx4 v[6:7], off
	v_lshl_add_u64 v[2:3], v[2:3], 0, s[12:13]
	s_mov_b32 m0, s48
	s_add_u32 s20, s30, 0x40080
	global_load_lds_dwordx4 v[2:3], off
	v_lshl_add_u64 v[2:3], v[4:5], 0, s[12:13]
	s_mov_b32 m0, s49
	s_addc_u32 s21, s31, 0
	global_load_lds_dwordx4 v[2:3], off
	s_add_i32 m0, s44, 0x1c000
	v_lshl_add_u64 v[2:3], s[20:21], 0, v[134:135]
	global_load_lds_dwordx4 v[2:3], off
	v_lshl_add_u64 v[2:3], s[20:21], 0, v[130:131]
	s_add_i32 m0, s44, 0x1e000
	s_cmpk_lt_u32 s5, 0x100
	global_load_lds_dwordx4 v[2:3], off
	v_bfe_u32 v3, v11, 4, 2
	v_and_b32_e32 v2, 15, v11
	v_lshlrev_b32_e32 v4, 4, v3
	v_lshl_or_b32 v1, s14, 6, v2
	v_lshl_or_b32 v2, v2, 6, v4
	v_lshlrev_b32_e32 v4, 2, v11
	v_and_b32_e32 v4, 32, v4
	v_bitop3_b32 v5, v2, s15, v4 bitop3:0xde
	v_bitop3_b32 v152, v2, s18, v4 bitop3:0xde
	v_and_b32_e32 v2, 16, v11
	v_lshlrev_b32_e32 v3, 2, v3
	v_add_u32_e32 v4, 60, v3
	v_cmp_eq_u32_e32 vcc, 0, v2
	s_waitcnt vmcnt(0)
	s_cselect_b64 s[14:15], -1, 0
	s_add_i32 s36, 0, 0x10000
	v_cndmask_b32_e32 v2, v4, v3, vcc
	v_lshl_add_u32 v153, s16, 4, v2
	v_lshlrev_b32_e32 v2, 14, v15
	v_and_b32_e32 v2, 0xffff8000, v2
	v_lshl_add_u32 v2, v14, 11, v2
	v_and_b32_e32 v3, 1, v15
	v_lshl_or_b32 v2, v3, 6, v2
	v_lshl_add_u32 v138, v16, 1, v2
	v_lshlrev_b32_e32 v2, 14, v10
	v_and_b32_e32 v2, 0xffff8000, v2
	v_lshl_add_u32 v2, v12, 11, v2
	v_and_b32_e32 v3, 1, v10
	v_lshl_or_b32 v2, v3, 6, v2
	s_add_i32 s37, 0, 0x14000
	s_sext_i32_i8 s1, s4
	v_mov_b32_e32 v139, v135
	v_lshl_add_u32 v140, v13, 1, v2
	v_mov_b32_e32 v141, v135
	v_mov_b64_e32 v[142:143], 0x1616
	v_mov_b64_e32 v[144:145], 0x1615
	v_add_u32_e32 v154, s36, v152
	v_add_u32_e32 v155, s37, v152
	v_add_u32_e32 v156, 0, v5
	s_movk_i32 s50, 0x1600
	s_mov_b32 s16, 0x3a800000
	s_mov_b32 s18, 0x358637bd
	s_mov_b32 s51, 0x800000
	s_barrier
	v_lshl_add_u32 v248, s0, 8, v1
	v_ashrrev_i32_e32 v249, 31, v248
	v_lshl_add_u64 v[248:249], v[248:249], 2, s[60:61]
	global_load_dword v241, v[248:249], off sc1
	global_load_dword v240, v[248:249], off offset:64 sc1
	global_load_dword v243, v[248:249], off offset:128 sc1
	global_load_dword v242, v[248:249], off offset:192 sc1
	global_load_dword v245, v[248:249], off offset:512 sc1
	global_load_dword v244, v[248:249], off offset:576 sc1
	global_load_dword v247, v[248:249], off offset:640 sc1
	global_load_dword v246, v[248:249], off offset:704 sc1
	s_branch .LBB0_599

.LBB0_605:
	s_ashr_i32 s23, s22, 31
	s_lshl_b64 s[24:25], s[22:23], 19
	s_add_u32 s24, s40, s24
	s_addc_u32 s25, s41, s25
	s_and_b64 s[26:27], s[4:5], exec
	s_cselect_b32 s23, s25, s29
	s_cselect_b32 s52, s24, s28
	s_ashr_i32 s21, s20, 31
	s_lshl_b64 s[26:27], s[20:21], 19
	s_add_u32 s26, s3, s26
	s_addc_u32 s27, s17, s27
	s_and_b64 s[38:39], s[4:5], exec
	s_cselect_b32 s21, s27, s31
	s_cselect_b32 s53, s26, s30
	s_cselect_b32 s38, s22, s0
	v_lshl_add_u32 v248, s38, 8, v1
	s_add_u32 s28, s28, 0x40080
	s_addc_u32 s29, s29, 0
	s_add_u32 s54, s30, 0x100
	s_addc_u32 s55, s31, 0
	s_mov_b32 s56, -2
	ds_read_b128 v[146:149], v154
	ds_read_b128 v[158:161], v154 offset:1024
	ds_read_b128 v[162:165], v154 offset:2048
	ds_read_b128 v[166:169], v154 offset:3072
	ds_read_b128 v[172:175], v155
	ds_read_b128 v[176:179], v155 offset:1024
	ds_read_b128 v[180:183], v155 offset:2048
	ds_read_b128 v[184:187], v155 offset:3072
	s_add_u32 s30, s28, 0xfffc0080
	s_addc_u32 s31, s29, -1
	s_cmp_eq_u32 s56, 12
	s_cselect_b32 s39, s23, s31
	s_cselect_b32 s38, s52, s30
	s_cselect_b32 s31, s21, s55
	s_cselect_b32 s30, s53, s54
	v_lshl_add_u64 v[150:151], s[28:29], 0, v[138:139]
	s_add_i32 m0, s44, 0xc000
	ds_read_b128 v[188:191], v156
	ds_read_b128 v[192:195], v156 offset:1024
	ds_read_b128 v[196:199], v156 offset:2048
	ds_read_b128 v[200:203], v156 offset:3072
	ds_read_b128 v[204:207], v156 offset:4096
	ds_read_b128 v[212:215], v156 offset:5120
	ds_read_b128 v[216:219], v156 offset:6144
	ds_read_b128 v[220:223], v156 offset:7168
	global_load_lds_dwordx4 v[150:151], off
	v_lshl_add_u64 v[150:151], s[28:29], 0, v[140:141]
	s_add_i32 m0, s44, 0xe000
	s_nop 0
	global_load_lds_dwordx4 v[150:151], off
	s_waitcnt vmcnt(22)
	s_waitcnt lgkmcnt(0)
	s_barrier
	s_setprio 1
	s_waitcnt lgkmcnt(0)
	v_mfma_f32_16x16x32_bf16 v[118:121], v[146:149], v[188:191], 0
	v_mfma_f32_16x16x32_bf16 v[126:129], v[162:165], v[188:191], 0
	v_mfma_f32_16x16x32_bf16 v[110:113], v[146:149], v[196:199], 0
	v_mfma_f32_16x16x32_bf16 v[106:109], v[162:165], v[196:199], 0
	v_mfma_f32_16x16x32_bf16 v[86:89], v[146:149], v[204:207], 0
	v_mfma_f32_16x16x32_bf16 v[94:97], v[162:165], v[204:207], 0
	v_mfma_f32_16x16x32_bf16 v[78:81], v[146:149], v[216:219], 0
	v_mfma_f32_16x16x32_bf16 v[74:77], v[162:165], v[216:219], 0
	v_mfma_f32_16x16x32_bf16 v[118:121], v[158:161], v[192:195], v[118:121]
	v_mfma_f32_16x16x32_bf16 v[126:129], v[166:169], v[192:195], v[126:129]
	v_mfma_f32_16x16x32_bf16 v[110:113], v[158:161], v[200:203], v[110:113]
	v_mfma_f32_16x16x32_bf16 v[106:109], v[166:169], v[200:203], v[106:109]
	v_mfma_f32_16x16x32_bf16 v[86:89], v[158:161], v[212:215], v[86:89]
	v_mfma_f32_16x16x32_bf16 v[94:97], v[166:169], v[212:215], v[94:97]
	v_mfma_f32_16x16x32_bf16 v[78:81], v[158:161], v[220:223], v[78:81]
	v_mfma_f32_16x16x32_bf16 v[74:77], v[166:169], v[220:223], v[74:77]
	s_setprio 0
	s_setprio 1
	v_mfma_f32_16x16x32_bf16 v[114:117], v[172:175], v[188:191], 0
	v_mfma_f32_16x16x32_bf16 v[122:125], v[180:183], v[188:191], 0
	v_mfma_f32_16x16x32_bf16 v[102:105], v[172:175], v[196:199], 0
	v_mfma_f32_16x16x32_bf16 v[98:101], v[180:183], v[196:199], 0
	v_mfma_f32_16x16x32_bf16 v[82:85], v[172:175], v[204:207], 0
	v_mfma_f32_16x16x32_bf16 v[90:93], v[180:183], v[204:207], 0
	v_mfma_f32_16x16x32_bf16 v[70:73], v[172:175], v[216:219], 0
	v_mfma_f32_16x16x32_bf16 v[66:69], v[180:183], v[216:219], 0
	v_mfma_f32_16x16x32_bf16 v[114:117], v[176:179], v[192:195], v[114:117]
	v_mfma_f32_16x16x32_bf16 v[122:125], v[184:187], v[192:195], v[122:125]
	v_mfma_f32_16x16x32_bf16 v[102:105], v[176:179], v[200:203], v[102:105]
	v_mfma_f32_16x16x32_bf16 v[98:101], v[184:187], v[200:203], v[98:101]
	v_mfma_f32_16x16x32_bf16 v[82:85], v[176:179], v[212:215], v[82:85]
	v_mfma_f32_16x16x32_bf16 v[90:93], v[184:187], v[212:215], v[90:93]
	v_mfma_f32_16x16x32_bf16 v[70:73], v[176:179], v[220:223], v[70:73]
	v_mfma_f32_16x16x32_bf16 v[66:69], v[184:187], v[220:223], v[66:69]
	s_setprio 0
	s_barrier
	s_add_i32 s42, s36, s19
	v_lshl_add_u64 v[150:151], s[30:31], 0, v[134:135]
	s_mov_b32 m0, s42
	ds_read_b128 v[188:191], v156 offset:16384
	ds_read_b128 v[192:195], v156 offset:17408
	ds_read_b128 v[196:199], v156 offset:18432
	ds_read_b128 v[200:203], v156 offset:19456
	ds_read_b128 v[204:207], v156 offset:20480
	ds_read_b128 v[212:215], v156 offset:21504
	ds_read_b128 v[216:219], v156 offset:22528
	ds_read_b128 v[220:223], v156 offset:23552
	global_load_lds_dwordx4 v[150:151], off
	s_add_i32 m0, s42, 0x2000
	s_add_u32 s42, s30, 0x40000
	v_lshl_add_u64 v[208:209], s[30:31], 0, v[130:131]
	s_addc_u32 s43, s31, 0
	s_add_i32 s57, s37, s19
	global_load_lds_dwordx4 v[208:209], off
	v_lshl_add_u64 v[224:225], s[42:43], 0, v[134:135]
	s_mov_b32 m0, s57
	v_lshl_add_u64 v[226:227], s[38:39], 0, v[132:133]
	global_load_lds_dwordx4 v[224:225], off
	v_lshl_add_u64 v[224:225], s[42:43], 0, v[130:131]
	s_add_i32 m0, s57, 0x2000
	s_nop 0
	global_load_lds_dwordx4 v[224:225], off
	v_lshl_add_u64 v[224:225], s[38:39], 0, v[136:137]
	s_mov_b32 m0, s44
	s_nop 0
	global_load_lds_dwordx4 v[224:225], off
	s_mov_b32 m0, s45
	s_nop 0
	global_load_lds_dwordx4 v[226:227], off
	s_waitcnt vmcnt(22)
	s_waitcnt lgkmcnt(0)
	s_barrier
	s_setprio 1
	s_waitcnt lgkmcnt(0)
	v_mfma_f32_16x16x32_bf16 v[58:61], v[146:149], v[188:191], 0
	v_mfma_f32_16x16x32_bf16 v[62:65], v[162:165], v[188:191], 0
	v_mfma_f32_16x16x32_bf16 v[46:49], v[146:149], v[196:199], 0
	v_mfma_f32_16x16x32_bf16 v[42:45], v[162:165], v[196:199], 0
	v_mfma_f32_16x16x32_bf16 v[22:25], v[146:149], v[204:207], 0
	v_mfma_f32_16x16x32_bf16 v[30:33], v[162:165], v[204:207], 0
	v_mfma_f32_16x16x32_bf16 v[14:17], v[146:149], v[216:219], 0
	v_mfma_f32_16x16x32_bf16 v[10:13], v[162:165], v[216:219], 0
	v_mfma_f32_16x16x32_bf16 v[58:61], v[158:161], v[192:195], v[58:61]
	v_mfma_f32_16x16x32_bf16 v[62:65], v[166:169], v[192:195], v[62:65]
	v_mfma_f32_16x16x32_bf16 v[46:49], v[158:161], v[200:203], v[46:49]
	v_mfma_f32_16x16x32_bf16 v[42:45], v[166:169], v[200:203], v[42:45]
	v_mfma_f32_16x16x32_bf16 v[22:25], v[158:161], v[212:215], v[22:25]
	v_mfma_f32_16x16x32_bf16 v[30:33], v[166:169], v[212:215], v[30:33]
	v_mfma_f32_16x16x32_bf16 v[14:17], v[158:161], v[220:223], v[14:17]
	v_mfma_f32_16x16x32_bf16 v[10:13], v[166:169], v[220:223], v[10:13]
	s_setprio 0
	s_setprio 1
	v_mfma_f32_16x16x32_bf16 v[50:53], v[172:175], v[188:191], 0
	v_mfma_f32_16x16x32_bf16 v[54:57], v[180:183], v[188:191], 0
	v_mfma_f32_16x16x32_bf16 v[38:41], v[172:175], v[196:199], 0
	v_mfma_f32_16x16x32_bf16 v[34:37], v[180:183], v[196:199], 0
	v_mfma_f32_16x16x32_bf16 v[18:21], v[172:175], v[204:207], 0
	v_mfma_f32_16x16x32_bf16 v[26:29], v[180:183], v[204:207], 0
	v_mfma_f32_16x16x32_bf16 v[6:9], v[172:175], v[216:219], 0
	v_mfma_f32_16x16x32_bf16 v[2:5], v[180:183], v[216:219], 0
	v_mfma_f32_16x16x32_bf16 v[50:53], v[176:179], v[192:195], v[50:53]
	v_mfma_f32_16x16x32_bf16 v[54:57], v[184:187], v[192:195], v[54:57]
	v_mfma_f32_16x16x32_bf16 v[38:41], v[176:179], v[200:203], v[38:41]
	v_mfma_f32_16x16x32_bf16 v[34:37], v[184:187], v[200:203], v[34:37]
	v_mfma_f32_16x16x32_bf16 v[18:21], v[176:179], v[212:215], v[18:21]
	v_mfma_f32_16x16x32_bf16 v[26:29], v[184:187], v[212:215], v[26:29]
	v_mfma_f32_16x16x32_bf16 v[6:9], v[176:179], v[220:223], v[6:9]
	v_mfma_f32_16x16x32_bf16 v[2:5], v[184:187], v[220:223], v[2:5]
	s_setprio 0
	s_barrier
	s_add_i32 s42, 0, 0x18000
	v_add_u32_e32 v157, s42, v152
	s_add_i32 s43, 0, 0x1c000
	ds_read_b128 v[146:149], v157
	ds_read_b128 v[158:161], v157 offset:1024
	ds_read_b128 v[162:165], v157 offset:2048
	ds_read_b128 v[166:169], v157 offset:3072
	v_add_u32_e32 v157, s43, v152
	ds_read_b128 v[172:175], v157
	ds_read_b128 v[176:179], v157 offset:1024
	ds_read_b128 v[180:183], v157 offset:2048
	ds_read_b128 v[184:187], v157 offset:3072
	s_add_u32 s38, s38, 0x40000
	s_addc_u32 s39, s39, 0
	s_mov_b32 m0, s33
	v_lshl_add_u64 v[228:229], s[38:39], 0, v[136:137]
	ds_read_b128 v[188:191], v156 offset:32768
	ds_read_b128 v[192:195], v156 offset:33792
	ds_read_b128 v[196:199], v156 offset:34816
	ds_read_b128 v[200:203], v156 offset:35840
	ds_read_b128 v[204:207], v156 offset:36864
	ds_read_b128 v[212:215], v156 offset:37888
	ds_read_b128 v[216:219], v156 offset:38912
	ds_read_b128 v[220:223], v156 offset:39936
	global_load_lds_dwordx4 v[228:229], off
	v_lshl_add_u64 v[228:229], s[38:39], 0, v[132:133]
	s_mov_b32 m0, s46
	s_nop 0
	global_load_lds_dwordx4 v[228:229], off
	s_waitcnt vmcnt(8)
	s_waitcnt lgkmcnt(0)
	s_barrier
	s_setprio 1
	s_waitcnt lgkmcnt(0)
	v_mfma_f32_16x16x32_bf16 v[118:121], v[146:149], v[188:191], v[118:121]
	v_mfma_f32_16x16x32_bf16 v[126:129], v[162:165], v[188:191], v[126:129]
	v_mfma_f32_16x16x32_bf16 v[110:113], v[146:149], v[196:199], v[110:113]
	v_mfma_f32_16x16x32_bf16 v[106:109], v[162:165], v[196:199], v[106:109]
	v_mfma_f32_16x16x32_bf16 v[86:89], v[146:149], v[204:207], v[86:89]
	v_mfma_f32_16x16x32_bf16 v[94:97], v[162:165], v[204:207], v[94:97]
	v_mfma_f32_16x16x32_bf16 v[78:81], v[146:149], v[216:219], v[78:81]
	v_mfma_f32_16x16x32_bf16 v[74:77], v[162:165], v[216:219], v[74:77]
	v_mfma_f32_16x16x32_bf16 v[118:121], v[158:161], v[192:195], v[118:121]
	v_mfma_f32_16x16x32_bf16 v[126:129], v[166:169], v[192:195], v[126:129]
	v_mfma_f32_16x16x32_bf16 v[110:113], v[158:161], v[200:203], v[110:113]
	v_mfma_f32_16x16x32_bf16 v[106:109], v[166:169], v[200:203], v[106:109]
	v_mfma_f32_16x16x32_bf16 v[86:89], v[158:161], v[212:215], v[86:89]
	v_mfma_f32_16x16x32_bf16 v[94:97], v[166:169], v[212:215], v[94:97]
	v_mfma_f32_16x16x32_bf16 v[78:81], v[158:161], v[220:223], v[78:81]
	v_mfma_f32_16x16x32_bf16 v[74:77], v[166:169], v[220:223], v[74:77]
	s_setprio 0
	s_setprio 1
	v_mfma_f32_16x16x32_bf16 v[114:117], v[172:175], v[188:191], v[114:117]
	v_mfma_f32_16x16x32_bf16 v[122:125], v[180:183], v[188:191], v[122:125]
	v_mfma_f32_16x16x32_bf16 v[102:105], v[172:175], v[196:199], v[102:105]
	v_mfma_f32_16x16x32_bf16 v[98:101], v[180:183], v[196:199], v[98:101]
	v_mfma_f32_16x16x32_bf16 v[82:85], v[172:175], v[204:207], v[82:85]
	v_mfma_f32_16x16x32_bf16 v[90:93], v[180:183], v[204:207], v[90:93]
	v_mfma_f32_16x16x32_bf16 v[70:73], v[172:175], v[216:219], v[70:73]
	v_mfma_f32_16x16x32_bf16 v[66:69], v[180:183], v[216:219], v[66:69]
	v_mfma_f32_16x16x32_bf16 v[114:117], v[176:179], v[192:195], v[114:117]
	v_mfma_f32_16x16x32_bf16 v[122:125], v[184:187], v[192:195], v[122:125]
	v_mfma_f32_16x16x32_bf16 v[102:105], v[176:179], v[200:203], v[102:105]
	v_mfma_f32_16x16x32_bf16 v[98:101], v[184:187], v[200:203], v[98:101]
	v_mfma_f32_16x16x32_bf16 v[82:85], v[176:179], v[212:215], v[82:85]
	v_mfma_f32_16x16x32_bf16 v[90:93], v[184:187], v[212:215], v[90:93]
	v_mfma_f32_16x16x32_bf16 v[70:73], v[176:179], v[220:223], v[70:73]
	v_mfma_f32_16x16x32_bf16 v[66:69], v[184:187], v[220:223], v[66:69]
	s_setprio 0
	s_barrier
	s_add_i32 s38, s42, s19
	v_lshl_add_u64 v[150:151], v[150:151], 0, s[12:13]
	s_mov_b32 m0, s38
	ds_read_b128 v[188:191], v156 offset:49152
	ds_read_b128 v[192:195], v156 offset:50176
	ds_read_b128 v[196:199], v156 offset:51200
	ds_read_b128 v[200:203], v156 offset:52224
	ds_read_b128 v[204:207], v156 offset:53248
	ds_read_b128 v[212:215], v156 offset:54272
	ds_read_b128 v[216:219], v156 offset:55296
	ds_read_b128 v[220:223], v156 offset:56320
	global_load_lds_dwordx4 v[150:151], off
	s_add_i32 m0, s38, 0x2000
	s_add_u32 s30, s30, 0x40080
	v_lshl_add_u64 v[150:151], v[208:209], 0, s[12:13]
	s_addc_u32 s31, s31, 0
	s_add_i32 s38, s43, s19
	global_load_lds_dwordx4 v[150:151], off
	v_lshl_add_u64 v[150:151], s[30:31], 0, v[134:135]
	s_mov_b32 m0, s38
	s_nop 0
	global_load_lds_dwordx4 v[150:151], off
	v_lshl_add_u64 v[150:151], s[30:31], 0, v[130:131]
	s_add_i32 m0, s38, 0x2000
	s_nop 0
	global_load_lds_dwordx4 v[150:151], off
	v_lshl_add_u64 v[150:151], v[224:225], 0, s[12:13]
	s_mov_b32 m0, s48
	s_nop 0
	global_load_lds_dwordx4 v[150:151], off
	v_lshl_add_u64 v[150:151], v[226:227], 0, s[12:13]
	s_mov_b32 m0, s49
	s_nop 0
	global_load_lds_dwordx4 v[150:151], off
	s_waitcnt vmcnt(8)
	s_waitcnt lgkmcnt(0)
	s_barrier
	s_setprio 1
	s_waitcnt lgkmcnt(0)
	v_mfma_f32_16x16x32_bf16 v[58:61], v[146:149], v[188:191], v[58:61]
	v_mfma_f32_16x16x32_bf16 v[62:65], v[162:165], v[188:191], v[62:65]
	v_mfma_f32_16x16x32_bf16 v[46:49], v[146:149], v[196:199], v[46:49]
	v_mfma_f32_16x16x32_bf16 v[42:45], v[162:165], v[196:199], v[42:45]
	v_mfma_f32_16x16x32_bf16 v[22:25], v[146:149], v[204:207], v[22:25]
	v_mfma_f32_16x16x32_bf16 v[30:33], v[162:165], v[204:207], v[30:33]
	v_mfma_f32_16x16x32_bf16 v[14:17], v[146:149], v[216:219], v[14:17]
	v_mfma_f32_16x16x32_bf16 v[10:13], v[162:165], v[216:219], v[10:13]
	v_mfma_f32_16x16x32_bf16 v[58:61], v[158:161], v[192:195], v[58:61]
	v_mfma_f32_16x16x32_bf16 v[62:65], v[166:169], v[192:195], v[62:65]
	v_mfma_f32_16x16x32_bf16 v[46:49], v[158:161], v[200:203], v[46:49]
	v_mfma_f32_16x16x32_bf16 v[42:45], v[166:169], v[200:203], v[42:45]
	v_mfma_f32_16x16x32_bf16 v[22:25], v[158:161], v[212:215], v[22:25]
	v_mfma_f32_16x16x32_bf16 v[30:33], v[166:169], v[212:215], v[30:33]
	v_mfma_f32_16x16x32_bf16 v[14:17], v[158:161], v[220:223], v[14:17]
	v_mfma_f32_16x16x32_bf16 v[10:13], v[166:169], v[220:223], v[10:13]
	s_setprio 0
	s_setprio 1
	v_mfma_f32_16x16x32_bf16 v[50:53], v[172:175], v[188:191], v[50:53]
	v_mfma_f32_16x16x32_bf16 v[54:57], v[180:183], v[188:191], v[54:57]
	v_mfma_f32_16x16x32_bf16 v[38:41], v[172:175], v[196:199], v[38:41]
	v_mfma_f32_16x16x32_bf16 v[34:37], v[180:183], v[196:199], v[34:37]
	v_mfma_f32_16x16x32_bf16 v[18:21], v[172:175], v[204:207], v[18:21]
	v_mfma_f32_16x16x32_bf16 v[26:29], v[180:183], v[204:207], v[26:29]
	v_mfma_f32_16x16x32_bf16 v[6:9], v[172:175], v[216:219], v[6:9]
	v_mfma_f32_16x16x32_bf16 v[2:5], v[180:183], v[216:219], v[2:5]
	v_mfma_f32_16x16x32_bf16 v[50:53], v[176:179], v[192:195], v[50:53]
	v_mfma_f32_16x16x32_bf16 v[54:57], v[184:187], v[192:195], v[54:57]
	v_mfma_f32_16x16x32_bf16 v[38:41], v[176:179], v[200:203], v[38:41]
	v_mfma_f32_16x16x32_bf16 v[34:37], v[184:187], v[200:203], v[34:37]
	v_mfma_f32_16x16x32_bf16 v[18:21], v[176:179], v[212:215], v[18:21]
	v_mfma_f32_16x16x32_bf16 v[26:29], v[184:187], v[212:215], v[26:29]
	v_mfma_f32_16x16x32_bf16 v[6:9], v[176:179], v[220:223], v[6:9]
	v_mfma_f32_16x16x32_bf16 v[2:5], v[184:187], v[220:223], v[2:5]
	s_setprio 0
	s_barrier
	s_add_i32 s56, s56, 2
	s_add_u32 s28, s28, 0x100
	s_addc_u32 s29, s29, 0
	s_add_u32 s54, s54, 0x100
	s_addc_u32 s55, s55, 0

.LBB0_679:
	s_mov_b64 s[16:17], 0x80
	s_and_b32 s22, s4, 3
	s_add_i32 m0, s60, 0x18000
	v_lshl_add_u64 v[8:9], v[8:9], 0, s[16:17]
	s_lshl_b32 s19, s7, 13
	s_lshl_b32 s20, s22, 12
	s_waitcnt vmcnt(2)
	s_barrier
	global_load_lds_dwordx4 v[8:9], off
	v_lshl_add_u64 v[4:5], v[4:5], 0, s[16:17]
	s_add_i32 m0, s60, 0x1a000
	s_add_i32 s65, s60, 0x8000
	s_add_i32 s66, s60, 0xa000
	global_load_lds_dwordx4 v[4:5], off
	v_lshl_add_u64 v[2:3], v[2:3], 0, s[16:17]
	s_mov_b32 m0, s65
	s_add_u32 s4, s52, 0xb0080
	global_load_lds_dwordx4 v[2:3], off
	v_lshl_add_u64 v[2:3], v[6:7], 0, s[16:17]
	s_mov_b32 m0, s66
	s_addc_u32 s5, s53, 0
	global_load_lds_dwordx4 v[2:3], off
	s_add_i32 m0, s60, 0x1c000
	v_lshl_add_u64 v[2:3], s[4:5], 0, v[164:165]
	global_load_lds_dwordx4 v[2:3], off
	v_lshl_add_u64 v[2:3], s[4:5], 0, v[168:169]
	s_add_i32 m0, s60, 0x1e000
	s_cmpk_lt_u32 s18, 0x100
	global_load_lds_dwordx4 v[2:3], off
	v_bfe_u32 v3, v1, 4, 2
	v_and_b32_e32 v2, 15, v1
	v_lshlrev_b32_e32 v5, 4, v3
	v_lshl_or_b32 v1, s7, 6, v2
	v_lshl_or_b32 v5, v2, 6, v5
	v_lshlrev_b32_e32 v2, 2, v2
	v_and_b32_e32 v6, 32, v2
	v_bitop3_b32 v7, v5, s19, v6 bitop3:0xde
	s_cselect_b64 s[18:19], -1, 0
	v_lshl_add_u64 v[172:173], s[10:11], 0, v[170:171]
	s_add_i32 s10, 0, 0x20000
	s_lshl_b32 s11, s22, 2
	s_lshl_b32 s7, s7, 8
	s_add_i32 s36, s10, s11
	v_add_u32_e32 v210, s10, v170
	s_add_i32 s10, s10, s7
	v_lshlrev_b32_e32 v4, 3, v3
	v_cmp_eq_u32_e64 s[4:5], 0, v3
	v_add_u32_e32 v212, s10, v2
	v_lshrrev_b32_e32 v3, 1, v10
	v_mul_lo_u32 v2, v12, s6
	s_mov_b32 s7, 0xb000
	v_mad_u64_u32 v[2:3], s[10:11], v3, s7, v[2:3]
	v_or_b32_e32 v2, v2, v11
	v_add_lshl_u32 v170, v2, v13, 1
	v_lshrrev_b32_e32 v3, 1, v14
	v_mul_lo_u32 v2, v15, s6
	v_mad_u64_u32 v[2:3], s[6:7], v3, s7, v[2:3]
	v_bitop3_b32 v208, v5, s20, v6 bitop3:0xde
	s_mov_b64 s[20:21], 0xb0080
	s_waitcnt vmcnt(0)
	v_or_b32_e32 v2, v2, v16
	v_lshl_or_b32 v209, s22, 5, v4
	v_lshlrev_b32_e32 v4, 4, v1
	v_mul_i32_i24_e32 v5, -12, v0
	v_lshl_add_u64 v[174:175], v[170:171], 0, s[20:21]
	v_add_lshl_u32 v170, v2, v17, 1
	s_add_i32 s67, 0, 0x10000
	s_add_i32 s68, 0, 0x14000
	v_lshl_add_u64 v[176:177], v[170:171], 0, s[20:21]
	v_mov_b64_e32 v[178:179], 0x3ff
	v_add_u32_e32 v213, s67, v208
	v_add_u32_e32 v214, s68, v208
	v_add_u32_e32 v215, 0, v7
	s_mov_b64 s[10:11], 0x40000
	s_mov_b64 s[20:21], 0x48000
	s_mov_b64 s[22:23], 0x50000
	s_mov_b64 s[24:25], 0x58000
	v_mov_b32_e32 v216, 0x358637bd
	s_mov_b32 s69, 0x800000
	v_add_u32_e32 v217, v210, v5
	s_mov_b32 s70, 0x80000
	s_mov_b32 s71, 0x90000
	s_mov_b32 s72, 0xa0000
	s_mov_b32 s73, 0xb0000
	s_mov_b64 s[26:27], 0x80000
	s_mov_b64 s[28:29], 0x90000
	s_mov_b64 s[30:31], 0xa0000
	v_add_u32_e32 v218, s36, v4
	s_barrier
	s_branch .LBB0_682

.LBB0_695:
	s_add_i32 s36, s33, -2
	s_add_u32 s37, s52, 0x100
	s_addc_u32 s39, s53, 0
	s_mov_b32 s47, 0
	s_waitcnt vmcnt(0)
	ds_read_b128 v[130:133], v213
	ds_read_b128 v[134:137], v213 offset:1024
	ds_read_b128 v[138:141], v213 offset:2048
	ds_read_b128 v[142:145], v213 offset:3072
	ds_read_b128 v[146:149], v214
	ds_read_b128 v[150:153], v214 offset:1024
	ds_read_b128 v[154:157], v214 offset:2048
	ds_read_b128 v[158:161], v214 offset:3072
	s_add_i32 s49, s47, 2
	s_add_u32 s52, s50, 0x100
	s_addc_u32 s53, s51, 0
	s_cmp_eq_u32 s36, s47
	s_cselect_b32 s57, s43, s53
	s_cselect_b32 s56, s42, s52
	s_cselect_b32 s55, s45, s39
	s_cselect_b32 s54, s44, s37
	v_lshl_add_u64 v[224:225], s[50:51], 0, v[174:175]
	s_add_i32 m0, s60, 0xc000
	ds_read_b128 v[180:183], v215
	ds_read_b128 v[184:187], v215 offset:1024
	ds_read_b128 v[188:191], v215 offset:2048
	ds_read_b128 v[192:195], v215 offset:3072
	ds_read_b128 v[196:199], v215 offset:4096
	ds_read_b128 v[200:203], v215 offset:5120
	ds_read_b128 v[204:207], v215 offset:6144
	ds_read_b128 v[220:223], v215 offset:7168
	global_load_lds_dwordx4 v[224:225], off
	v_lshl_add_u64 v[224:225], s[50:51], 0, v[176:177]
	s_add_i32 m0, s60, 0xe000
	s_nop 0
	global_load_lds_dwordx4 v[224:225], off
	s_waitcnt vmcnt(38)
	s_waitcnt lgkmcnt(0)
	s_barrier
	s_setprio 1
	s_waitcnt lgkmcnt(0)
	v_mfma_f32_16x16x32_bf16 v[126:129], v[130:133], v[180:183], 0
	v_mfma_f32_16x16x32_bf16 v[122:125], v[138:141], v[180:183], 0
	v_mfma_f32_16x16x32_bf16 v[118:121], v[130:133], v[188:191], 0
	v_mfma_f32_16x16x32_bf16 v[114:117], v[138:141], v[188:191], 0
	v_mfma_f32_16x16x32_bf16 v[102:105], v[130:133], v[196:199], 0
	v_mfma_f32_16x16x32_bf16 v[98:101], v[138:141], v[196:199], 0
	v_mfma_f32_16x16x32_bf16 v[86:89], v[130:133], v[204:207], 0
	v_mfma_f32_16x16x32_bf16 v[82:85], v[138:141], v[204:207], 0
	v_mfma_f32_16x16x32_bf16 v[126:129], v[134:137], v[184:187], v[126:129]
	v_mfma_f32_16x16x32_bf16 v[122:125], v[142:145], v[184:187], v[122:125]
	v_mfma_f32_16x16x32_bf16 v[118:121], v[134:137], v[192:195], v[118:121]
	v_mfma_f32_16x16x32_bf16 v[114:117], v[142:145], v[192:195], v[114:117]
	v_mfma_f32_16x16x32_bf16 v[102:105], v[134:137], v[200:203], v[102:105]
	v_mfma_f32_16x16x32_bf16 v[98:101], v[142:145], v[200:203], v[98:101]
	v_mfma_f32_16x16x32_bf16 v[86:89], v[134:137], v[220:223], v[86:89]
	v_mfma_f32_16x16x32_bf16 v[82:85], v[142:145], v[220:223], v[82:85]
	s_setprio 0
	s_setprio 1
	v_mfma_f32_16x16x32_bf16 v[110:113], v[146:149], v[180:183], 0
	v_mfma_f32_16x16x32_bf16 v[106:109], v[154:157], v[180:183], 0
	v_mfma_f32_16x16x32_bf16 v[94:97], v[146:149], v[188:191], 0
	v_mfma_f32_16x16x32_bf16 v[90:93], v[154:157], v[188:191], 0
	v_mfma_f32_16x16x32_bf16 v[78:81], v[146:149], v[196:199], 0
	v_mfma_f32_16x16x32_bf16 v[74:77], v[154:157], v[196:199], 0
	v_mfma_f32_16x16x32_bf16 v[70:73], v[146:149], v[204:207], 0
	v_mfma_f32_16x16x32_bf16 v[66:69], v[154:157], v[204:207], 0
	v_mfma_f32_16x16x32_bf16 v[110:113], v[150:153], v[184:187], v[110:113]
	v_mfma_f32_16x16x32_bf16 v[106:109], v[158:161], v[184:187], v[106:109]
	v_mfma_f32_16x16x32_bf16 v[94:97], v[150:153], v[192:195], v[94:97]
	v_mfma_f32_16x16x32_bf16 v[90:93], v[158:161], v[192:195], v[90:93]
	v_mfma_f32_16x16x32_bf16 v[78:81], v[150:153], v[200:203], v[78:81]
	v_mfma_f32_16x16x32_bf16 v[74:77], v[158:161], v[200:203], v[74:77]
	v_mfma_f32_16x16x32_bf16 v[70:73], v[150:153], v[220:223], v[70:73]
	v_mfma_f32_16x16x32_bf16 v[66:69], v[158:161], v[220:223], v[66:69]
	s_setprio 0
	s_barrier
	s_add_i32 s47, s67, s59
	v_lshl_add_u64 v[224:225], s[54:55], 0, v[164:165]
	s_mov_b32 m0, s47
	ds_read_b128 v[180:183], v215 offset:16384
	ds_read_b128 v[184:187], v215 offset:17408
	ds_read_b128 v[188:191], v215 offset:18432
	ds_read_b128 v[192:195], v215 offset:19456
	ds_read_b128 v[196:199], v215 offset:20480
	ds_read_b128 v[200:203], v215 offset:21504
	ds_read_b128 v[204:207], v215 offset:22528
	ds_read_b128 v[220:223], v215 offset:23552
	global_load_lds_dwordx4 v[224:225], off
	s_add_i32 m0, s47, 0x2000
	s_add_u32 s50, s54, 0xb0000
	v_lshl_add_u64 v[226:227], s[54:55], 0, v[168:169]
	s_addc_u32 s51, s55, 0
	s_add_i32 s47, s68, s59
	global_load_lds_dwordx4 v[226:227], off
	v_lshl_add_u64 v[228:229], s[50:51], 0, v[164:165]
	s_mov_b32 m0, s47
	v_lshl_add_u64 v[230:231], s[56:57], 0, v[166:167]
	global_load_lds_dwordx4 v[228:229], off
	v_lshl_add_u64 v[228:229], s[50:51], 0, v[168:169]
	s_add_i32 m0, s47, 0x2000
	s_nop 0
	global_load_lds_dwordx4 v[228:229], off
	v_lshl_add_u64 v[228:229], s[56:57], 0, v[162:163]
	s_mov_b32 m0, s60
	s_nop 0
	global_load_lds_dwordx4 v[228:229], off
	s_mov_b32 m0, s61
	s_nop 0
	global_load_lds_dwordx4 v[230:231], off
	s_waitcnt vmcnt(38)
	s_waitcnt lgkmcnt(0)
	s_barrier
	s_setprio 1
	s_waitcnt lgkmcnt(0)
	v_mfma_f32_16x16x32_bf16 v[62:65], v[130:133], v[180:183], 0
	v_mfma_f32_16x16x32_bf16 v[58:61], v[138:141], v[180:183], 0
	v_mfma_f32_16x16x32_bf16 v[54:57], v[130:133], v[188:191], 0
	v_mfma_f32_16x16x32_bf16 v[50:53], v[138:141], v[188:191], 0
	v_mfma_f32_16x16x32_bf16 v[38:41], v[130:133], v[196:199], 0
	v_mfma_f32_16x16x32_bf16 v[34:37], v[138:141], v[196:199], 0
	v_mfma_f32_16x16x32_bf16 v[22:25], v[130:133], v[204:207], 0
	v_mfma_f32_16x16x32_bf16 v[18:21], v[138:141], v[204:207], 0
	v_mfma_f32_16x16x32_bf16 v[62:65], v[134:137], v[184:187], v[62:65]
	v_mfma_f32_16x16x32_bf16 v[58:61], v[142:145], v[184:187], v[58:61]
	v_mfma_f32_16x16x32_bf16 v[54:57], v[134:137], v[192:195], v[54:57]
	v_mfma_f32_16x16x32_bf16 v[50:53], v[142:145], v[192:195], v[50:53]
	v_mfma_f32_16x16x32_bf16 v[38:41], v[134:137], v[200:203], v[38:41]
	v_mfma_f32_16x16x32_bf16 v[34:37], v[142:145], v[200:203], v[34:37]
	v_mfma_f32_16x16x32_bf16 v[22:25], v[134:137], v[220:223], v[22:25]
	v_mfma_f32_16x16x32_bf16 v[18:21], v[142:145], v[220:223], v[18:21]
	s_setprio 0
	s_setprio 1
	v_mfma_f32_16x16x32_bf16 v[46:49], v[146:149], v[180:183], 0
	v_mfma_f32_16x16x32_bf16 v[42:45], v[154:157], v[180:183], 0
	v_mfma_f32_16x16x32_bf16 v[30:33], v[146:149], v[188:191], 0
	v_mfma_f32_16x16x32_bf16 v[26:29], v[154:157], v[188:191], 0
	v_mfma_f32_16x16x32_bf16 v[14:17], v[146:149], v[196:199], 0
	v_mfma_f32_16x16x32_bf16 v[10:13], v[154:157], v[196:199], 0
	v_mfma_f32_16x16x32_bf16 v[6:9], v[146:149], v[204:207], 0
	v_mfma_f32_16x16x32_bf16 v[2:5], v[154:157], v[204:207], 0
	v_mfma_f32_16x16x32_bf16 v[46:49], v[150:153], v[184:187], v[46:49]
	v_mfma_f32_16x16x32_bf16 v[42:45], v[158:161], v[184:187], v[42:45]
	v_mfma_f32_16x16x32_bf16 v[30:33], v[150:153], v[192:195], v[30:33]
	v_mfma_f32_16x16x32_bf16 v[26:29], v[158:161], v[192:195], v[26:29]
	v_mfma_f32_16x16x32_bf16 v[14:17], v[150:153], v[200:203], v[14:17]
	v_mfma_f32_16x16x32_bf16 v[10:13], v[158:161], v[200:203], v[10:13]
	v_mfma_f32_16x16x32_bf16 v[6:9], v[150:153], v[220:223], v[6:9]
	v_mfma_f32_16x16x32_bf16 v[2:5], v[158:161], v[220:223], v[2:5]
	s_setprio 0
	s_barrier
	s_add_i32 s47, 0, 0x18000
	s_add_i32 s84, 0, 0x1c000
	v_add_u32_e32 v142, s47, v208
	v_add_u32_e32 v158, s84, v208
	ds_read_b128 v[130:133], v142
	ds_read_b128 v[134:137], v142 offset:1024
	ds_read_b128 v[138:141], v142 offset:2048
	ds_read_b128 v[142:145], v142 offset:3072
	ds_read_b128 v[146:149], v158
	ds_read_b128 v[150:153], v158 offset:1024
	ds_read_b128 v[154:157], v158 offset:2048
	ds_read_b128 v[158:161], v158 offset:3072
	s_add_u32 s50, s56, 0xb0000
	s_addc_u32 s51, s57, 0
	s_mov_b32 m0, s62
	v_lshl_add_u64 v[232:233], s[50:51], 0, v[162:163]
	ds_read_b128 v[180:183], v215 offset:32768
	ds_read_b128 v[184:187], v215 offset:33792
	ds_read_b128 v[188:191], v215 offset:34816
	ds_read_b128 v[192:195], v215 offset:35840
	ds_read_b128 v[196:199], v215 offset:36864
	ds_read_b128 v[200:203], v215 offset:37888
	ds_read_b128 v[204:207], v215 offset:38912
	ds_read_b128 v[220:223], v215 offset:39936
	global_load_lds_dwordx4 v[232:233], off
	v_lshl_add_u64 v[232:233], s[50:51], 0, v[166:167]
	s_mov_b32 m0, s63
	s_nop 0
	global_load_lds_dwordx4 v[232:233], off
	s_waitcnt vmcnt(8)
	s_waitcnt lgkmcnt(0)
	s_barrier
	s_setprio 1
	s_waitcnt lgkmcnt(0)
	v_mfma_f32_16x16x32_bf16 v[126:129], v[130:133], v[180:183], v[126:129]
	v_mfma_f32_16x16x32_bf16 v[122:125], v[138:141], v[180:183], v[122:125]
	v_mfma_f32_16x16x32_bf16 v[118:121], v[130:133], v[188:191], v[118:121]
	v_mfma_f32_16x16x32_bf16 v[114:117], v[138:141], v[188:191], v[114:117]
	v_mfma_f32_16x16x32_bf16 v[102:105], v[130:133], v[196:199], v[102:105]
	v_mfma_f32_16x16x32_bf16 v[98:101], v[138:141], v[196:199], v[98:101]
	v_mfma_f32_16x16x32_bf16 v[86:89], v[130:133], v[204:207], v[86:89]
	v_mfma_f32_16x16x32_bf16 v[82:85], v[138:141], v[204:207], v[82:85]
	v_mfma_f32_16x16x32_bf16 v[126:129], v[134:137], v[184:187], v[126:129]
	v_mfma_f32_16x16x32_bf16 v[122:125], v[142:145], v[184:187], v[122:125]
	v_mfma_f32_16x16x32_bf16 v[118:121], v[134:137], v[192:195], v[118:121]
	v_mfma_f32_16x16x32_bf16 v[114:117], v[142:145], v[192:195], v[114:117]
	v_mfma_f32_16x16x32_bf16 v[102:105], v[134:137], v[200:203], v[102:105]
	v_mfma_f32_16x16x32_bf16 v[98:101], v[142:145], v[200:203], v[98:101]
	v_mfma_f32_16x16x32_bf16 v[86:89], v[134:137], v[220:223], v[86:89]
	v_mfma_f32_16x16x32_bf16 v[82:85], v[142:145], v[220:223], v[82:85]
	s_setprio 0
	s_setprio 1
	v_mfma_f32_16x16x32_bf16 v[110:113], v[146:149], v[180:183], v[110:113]
	v_mfma_f32_16x16x32_bf16 v[106:109], v[154:157], v[180:183], v[106:109]
	v_mfma_f32_16x16x32_bf16 v[94:97], v[146:149], v[188:191], v[94:97]
	v_mfma_f32_16x16x32_bf16 v[90:93], v[154:157], v[188:191], v[90:93]
	v_mfma_f32_16x16x32_bf16 v[78:81], v[146:149], v[196:199], v[78:81]
	v_mfma_f32_16x16x32_bf16 v[74:77], v[154:157], v[196:199], v[74:77]
	v_mfma_f32_16x16x32_bf16 v[70:73], v[146:149], v[204:207], v[70:73]
	v_mfma_f32_16x16x32_bf16 v[66:69], v[154:157], v[204:207], v[66:69]
	v_mfma_f32_16x16x32_bf16 v[110:113], v[150:153], v[184:187], v[110:113]
	v_mfma_f32_16x16x32_bf16 v[106:109], v[158:161], v[184:187], v[106:109]
	v_mfma_f32_16x16x32_bf16 v[94:97], v[150:153], v[192:195], v[94:97]
	v_mfma_f32_16x16x32_bf16 v[90:93], v[158:161], v[192:195], v[90:93]
	v_mfma_f32_16x16x32_bf16 v[78:81], v[150:153], v[200:203], v[78:81]
	v_mfma_f32_16x16x32_bf16 v[74:77], v[158:161], v[200:203], v[74:77]
	v_mfma_f32_16x16x32_bf16 v[70:73], v[150:153], v[220:223], v[70:73]
	v_mfma_f32_16x16x32_bf16 v[66:69], v[158:161], v[220:223], v[66:69]
	s_setprio 0
	s_barrier
	s_add_i32 s47, s47, s59
	v_lshl_add_u64 v[224:225], v[224:225], 0, s[16:17]
	s_mov_b32 m0, s47
	ds_read_b128 v[180:183], v215 offset:49152
	ds_read_b128 v[184:187], v215 offset:50176
	ds_read_b128 v[188:191], v215 offset:51200
	ds_read_b128 v[192:195], v215 offset:52224
	ds_read_b128 v[196:199], v215 offset:53248
	ds_read_b128 v[200:203], v215 offset:54272
	ds_read_b128 v[204:207], v215 offset:55296
	ds_read_b128 v[220:223], v215 offset:56320
	global_load_lds_dwordx4 v[224:225], off
	s_add_i32 m0, s47, 0x2000
	s_add_u32 s50, s54, 0xb0080
	v_lshl_add_u64 v[224:225], v[226:227], 0, s[16:17]
	s_addc_u32 s51, s55, 0
	s_add_i32 s47, s84, s59
	global_load_lds_dwordx4 v[224:225], off
	v_lshl_add_u64 v[224:225], s[50:51], 0, v[164:165]
	s_mov_b32 m0, s47
	s_nop 0
	global_load_lds_dwordx4 v[224:225], off
	v_lshl_add_u64 v[224:225], s[50:51], 0, v[168:169]
	s_add_i32 m0, s47, 0x2000
	s_nop 0
	global_load_lds_dwordx4 v[224:225], off
	v_lshl_add_u64 v[224:225], v[228:229], 0, s[16:17]
	s_mov_b32 m0, s65
	s_nop 0
	global_load_lds_dwordx4 v[224:225], off
	v_lshl_add_u64 v[224:225], v[230:231], 0, s[16:17]
	s_mov_b32 m0, s66
	s_nop 0
	global_load_lds_dwordx4 v[224:225], off
	s_waitcnt vmcnt(8)
	s_waitcnt lgkmcnt(0)
	s_barrier
	s_setprio 1
	s_waitcnt lgkmcnt(0)
	v_mfma_f32_16x16x32_bf16 v[62:65], v[130:133], v[180:183], v[62:65]
	v_mfma_f32_16x16x32_bf16 v[58:61], v[138:141], v[180:183], v[58:61]
	v_mfma_f32_16x16x32_bf16 v[54:57], v[130:133], v[188:191], v[54:57]
	v_mfma_f32_16x16x32_bf16 v[50:53], v[138:141], v[188:191], v[50:53]
	v_mfma_f32_16x16x32_bf16 v[38:41], v[130:133], v[196:199], v[38:41]
	v_mfma_f32_16x16x32_bf16 v[34:37], v[138:141], v[196:199], v[34:37]
	v_mfma_f32_16x16x32_bf16 v[22:25], v[130:133], v[204:207], v[22:25]
	v_mfma_f32_16x16x32_bf16 v[18:21], v[138:141], v[204:207], v[18:21]
	v_mfma_f32_16x16x32_bf16 v[62:65], v[134:137], v[184:187], v[62:65]
	v_mfma_f32_16x16x32_bf16 v[58:61], v[142:145], v[184:187], v[58:61]
	v_mfma_f32_16x16x32_bf16 v[54:57], v[134:137], v[192:195], v[54:57]
	v_mfma_f32_16x16x32_bf16 v[50:53], v[142:145], v[192:195], v[50:53]
	v_mfma_f32_16x16x32_bf16 v[38:41], v[134:137], v[200:203], v[38:41]
	v_mfma_f32_16x16x32_bf16 v[34:37], v[142:145], v[200:203], v[34:37]
	v_mfma_f32_16x16x32_bf16 v[22:25], v[134:137], v[220:223], v[22:25]
	v_mfma_f32_16x16x32_bf16 v[18:21], v[142:145], v[220:223], v[18:21]
	s_setprio 0
	s_setprio 1
	v_mfma_f32_16x16x32_bf16 v[46:49], v[146:149], v[180:183], v[46:49]
	v_mfma_f32_16x16x32_bf16 v[42:45], v[154:157], v[180:183], v[42:45]
	v_mfma_f32_16x16x32_bf16 v[30:33], v[146:149], v[188:191], v[30:33]
	v_mfma_f32_16x16x32_bf16 v[26:29], v[154:157], v[188:191], v[26:29]
	v_mfma_f32_16x16x32_bf16 v[14:17], v[146:149], v[196:199], v[14:17]
	v_mfma_f32_16x16x32_bf16 v[10:13], v[154:157], v[196:199], v[10:13]
	v_mfma_f32_16x16x32_bf16 v[6:9], v[146:149], v[204:207], v[6:9]
	v_mfma_f32_16x16x32_bf16 v[2:5], v[154:157], v[204:207], v[2:5]
	v_mfma_f32_16x16x32_bf16 v[46:49], v[150:153], v[184:187], v[46:49]
	v_mfma_f32_16x16x32_bf16 v[42:45], v[158:161], v[184:187], v[42:45]
	v_mfma_f32_16x16x32_bf16 v[30:33], v[150:153], v[192:195], v[30:33]
	v_mfma_f32_16x16x32_bf16 v[26:29], v[158:161], v[192:195], v[26:29]
	v_mfma_f32_16x16x32_bf16 v[14:17], v[150:153], v[200:203], v[14:17]
	v_mfma_f32_16x16x32_bf16 v[10:13], v[158:161], v[200:203], v[10:13]
	v_mfma_f32_16x16x32_bf16 v[6:9], v[150:153], v[220:223], v[6:9]
	v_mfma_f32_16x16x32_bf16 v[2:5], v[158:161], v[220:223], v[2:5]
	s_setprio 0
	s_barrier
	s_add_u32 s37, s37, 0x100
	s_addc_u32 s39, s39, 0
	s_mov_b64 s[50:51], s[52:53]
	s_mov_b32 s47, s49
